# sample attention K/V/q loads re-laid out so each dwordx4 covers full 128B lines (lane c: dims 4c..4c+3 and 32+4c..), output stored as two 8B halves
# speedup vs baseline: 1.0031x; 1.0031x over previous
; __device__ __forceinline__ void p_attn_sample(const float* P, const float* ck, const float* cv, const float* relb, bf16* heads, const float* sbt, unsigned* qctr, volatile LAS unsigned* slot, int wave, int lane_in) {
;     ...
;         const int b = (int)(wt >> 2), t = wave & 3, h = 2 * (int)(wt & 3u) + (wave >> 2), sr = 4 * b + t, m = MP + sr, p = SEQ + t;
;         f32x4 q0 = *(const f32x4*)(P + (size_t)m * NINP + C_AQ + h * 64 + 8 * c), q1 = *(const f32x4*)(P + (size_t)m * NINP + C_AQ + h * 64 + 8 * c + 4);
;         q0 = q0 * 0.125f; q1 = q1 * 0.125f;
;         const float* knew = P + (size_t)(MP + b * DS) * NINP + C_AK + h * 64 + 8 * c; const float* kold = ck + ((size_t)b * SEQ * NH + h) * HD + 8 * c;
;         const float* vold = cv + ((size_t)b * SEQ * NH + h) * HD + 8 * c;
;         const float* sbh = sbt + h * 392;
;         float mx = -INFINITY, sum = 0.f; float acc[8];
; #pragma unroll
;         for (int j = 0; j < 8; ++j) acc[j] = 0.f;
;         f32x4 ak0[4], ak1[4], av0[4], av1[4], bk0[4], bk1[4], bv0[4], bv1[4]; float ab[4], bbv[4];
.LBB0_1241:
	v_readlane_b32 s48, v245, 21
	s_and_b64 vcc, exec, s[20:21]
	v_readlane_b32 s49, v245, 22
	s_cbranch_vccnz .LBB0_1287
	v_mov_b32_e32 v2, v196
	s_movk_i32 s19, 0x80
	v_ashrrev_i32_e32 v18, 3, v2
	v_readlane_b32 s0, v245, 0
	v_lshlrev_b32_e32 v3, 3, v2
	v_cmp_lt_i32_e32 vcc, s19, v18
	s_movk_i32 s24, 0x102
	s_bfe_u32 s27, s0, 0x20006
	s_lshr_b32 s16, s0, 8
	v_and_b32_e32 v154, 56, v3
	v_readlane_b32 s0, v245, 5
	v_cndmask_b32_e64 v3, 0, 1, vcc
	v_cmp_gt_i32_e32 vcc, s24, v18
	v_mov_b32_e32 v157, 0
	v_lshlrev_b32_e32 v156, 1, v154
	v_readlane_b32 s4, v245, 9
	v_readlane_b32 s5, v245, 10
	v_cndmask_b32_e32 v3, 2, v3, vcc
	v_mul_i32_i24_e32 v4, 0xffffff7f, v3
	v_lshl_add_u64 v[158:159], s[4:5], 0, v[156:157]
	v_cmp_gt_u32_e64 s[4:5], 8, v2
	v_min_i32_e32 v2, 0x182, v18
	v_lshlrev_b32_e32 v3, 1, v3
	s_or_b32 s18, s27, 0x800
	v_add_lshl_u32 v2, v4, v2, v3
	v_sub_u32_e32 v2, s18, v2
	v_ashrrev_i32_e32 v3, 31, v2
	v_readlane_b32 s1, v245, 6
	v_lshlrev_b64 v[162:163], 11, v[2:3]
	v_add_u32_e32 v3, 0xfffff800, v2
	s_movk_i32 s26, 0x3c00
	v_mad_u64_u32 v[164:165], s[0:1], v3, s26, 0
	s_movk_i32 s0, 0x78
	s_nop 0
	v_cmp_lt_i32_e32 vcc, s0, v18
	s_movk_i32 s0, 0xfa
	v_mov_b32_e32 v3, v157
	v_cndmask_b32_e64 v7, 0, 1, vcc
	v_cmp_gt_i32_e32 vcc, s0, v18
	v_lshlrev_b64 v[4:5], 11, v[2:3]
	v_add_u32_e32 v3, 8, v18
	v_cndmask_b32_e32 v7, 2, v7, vcc
	v_min_i32_e32 v6, 0x182, v3
	v_mul_i32_i24_e32 v8, 0xffffff7f, v7
	v_lshlrev_b32_e32 v7, 1, v7
	v_add_lshl_u32 v6, v8, v6, v7
	v_sub_u32_e32 v6, s18, v6
	v_ashrrev_i32_e32 v7, 31, v6
	v_lshlrev_b64 v[168:169], 11, v[6:7]
	v_add_u32_e32 v7, 0xfffff800, v6
	v_mad_u64_u32 v[170:171], s[0:1], v7, s26, 0
	s_movk_i32 s0, 0x70
	s_nop 0
	v_cmp_lt_i32_e32 vcc, s0, v18
	s_movk_i32 s0, 0xf2
	v_mov_b32_e32 v7, v157
	v_cndmask_b32_e64 v10, 0, 1, vcc
	v_cmp_gt_i32_e32 vcc, s0, v18
	v_min_i32_e32 v172, 0x187, v3
	v_add_u32_e32 v3, 16, v18
	v_cndmask_b32_e32 v10, 2, v10, vcc
	v_lshlrev_b64 v[8:9], 11, v[6:7]
	v_min_i32_e32 v7, 0x182, v3
	v_mul_i32_i24_e32 v11, 0xffffff7f, v10
	v_lshlrev_b32_e32 v10, 1, v10
	v_add_lshl_u32 v7, v11, v7, v10
	v_sub_u32_e32 v10, s18, v7
	v_add_u32_e32 v7, 0xfffff800, v10
	v_mad_u64_u32 v[176:177], s[0:1], v7, s26, 0
	v_ashrrev_i32_e32 v11, 31, v10
	s_movk_i32 s0, 0x68
	v_lshlrev_b64 v[174:175], 11, v[10:11]
	v_mov_b32_e32 v11, v157
	v_cmp_lt_i32_e32 vcc, s0, v18
	s_movk_i32 s0, 0xea
	v_lshlrev_b64 v[12:13], 11, v[10:11]
	v_cndmask_b32_e64 v11, 0, 1, vcc
	v_cmp_gt_i32_e32 vcc, s0, v18
	v_min_i32_e32 v178, 0x187, v3
	v_add_u32_e32 v3, 24, v18
	v_cndmask_b32_e32 v11, 2, v11, vcc
	v_min_i32_e32 v7, 0x182, v3
	v_mul_i32_i24_e32 v14, 0xffffff7f, v11
	v_lshlrev_b32_e32 v11, 1, v11
	v_add_lshl_u32 v7, v14, v7, v11
	v_sub_u32_e32 v14, s18, v7
	v_ashrrev_i32_e32 v15, 31, v14
	v_readlane_b32 s6, v245, 11
	v_readlane_b32 s7, v245, 12
	v_readlane_b32 s8, v245, 13
	v_readlane_b32 s9, v245, 14
	v_readlane_b32 s10, v245, 15
	v_readlane_b32 s11, v245, 16
	v_readlane_b32 s12, v245, 17
	v_readlane_b32 s13, v245, 18
	s_movk_i32 s25, 0x7ff
	v_lshlrev_b64 v[180:181], 11, v[14:15]
	v_mov_b32_e32 v15, v157
	v_lshl_add_u64 v[160:161], s[6:7], 0, v[156:157]
	v_min_i32_e32 v166, 0x187, v18
	v_add_u32_e32 v7, 0xfffff800, v14
	v_lshlrev_b64 v[16:17], 11, v[14:15]
	v_min_i32_e32 v184, 0x187, v3
	v_cmp_lt_i32_e64 s[6:7], s25, v2
	v_cmp_lt_i32_e64 s[8:9], s25, v6
	v_cmp_lt_i32_e64 s[10:11], s25, v10
	v_cmp_lt_i32_e64 s[12:13], s25, v14
	s_movk_i32 s17, 0x800
	v_ashrrev_i32_e32 v167, 31, v166
	v_ashrrev_i32_e32 v173, 31, v172
	v_ashrrev_i32_e32 v179, 31, v178
	v_mad_u64_u32 v[182:183], s[0:1], v7, s26, 0
	v_ashrrev_i32_e32 v185, 31, v184
	v_add_u32_e32 v155, 0x58, v18
	v_cndmask_b32_e64 v187, v163, v5, s[6:7]
	v_cndmask_b32_e64 v186, v162, v4, s[6:7]
	v_cndmask_b32_e64 v189, v169, v9, s[8:9]
	v_cndmask_b32_e64 v188, v168, v8, s[8:9]
	v_cndmask_b32_e64 v191, v175, v13, s[10:11]
	v_cndmask_b32_e64 v190, v174, v12, s[10:11]
	v_cndmask_b32_e64 v193, v181, v17, s[12:13]
	v_cndmask_b32_e64 v192, v180, v16, s[12:13]
	s_bitset1_b32 s27, 14
	s_mov_b32 s23, 0
	s_add_i32 s29, 0, 0x23f84
	s_mov_b32 s28, 0x3e000000
	s_mov_b64 s[30:31], 0xf000800
	s_mov_b64 s[38:39], 0x800
	v_mbcnt_hi_u32_b32 v197, -1, v1
	v_readlane_b32 s2, v245, 7
	v_readlane_b32 s3, v245, 8
	v_readlane_b32 s14, v245, 19
	v_readlane_b32 s15, v245, 20
	s_branch .LBB0_1245

; __device__ __forceinline__ void p_attn_sample(const float* P, const float* ck, const float* cv, const float* relb, bf16* heads, const float* sbt, unsigned* qctr, volatile LAS unsigned* slot, int wave, int lane_in) {
;     ...
;         __syncthreads(); if (threadIdx.x == 0) *slot = __hip_atomic_fetch_add(qctr, 1u, __ATOMIC_RELAXED, __HIP_MEMORY_SCOPE_AGENT); __syncthreads();
;         const unsigned wt = *slot; if (wt >= (unsigned)(DB * 4)) break;
;         const int b = (int)(wt >> 2), t = wave & 3, h = 2 * (int)(wt & 3u) + (wave >> 2), sr = 4 * b + t, m = MP + sr, p = SEQ + t;
;         f32x4 q0 = *(const f32x4*)(P + (size_t)m * NINP + C_AQ + h * 64 + 8 * c), q1 = *(const f32x4*)(P + (size_t)m * NINP + C_AQ + h * 64 + 8 * c + 4);
;         q0 = q0 * 0.125f; q1 = q1 * 0.125f;
;         const float* knew = P + (size_t)(MP + b * DS) * NINP + C_AK + h * 64 + 8 * c; const float* kold = ck + ((size_t)b * SEQ * NH + h) * HD + 8 * c;
;         const float* vold = cv + ((size_t)b * SEQ * NH + h) * HD + 8 * c;
;         const float* sbh = sbt + h * 392;
;         float mx = -INFINITY, sum = 0.f; float acc[8];
; #pragma unroll
;         for (int j = 0; j < 8; ++j) acc[j] = 0.f;
;         f32x4 ak0[4], ak1[4], av0[4], av1[4], bk0[4], bk1[4], bv0[4], bv1[4]; float ab[4], bbv[4];
;     ...
;         SLOADB(ak0, ak1, av0, av1, ab, 0)
.LBB0_1249:
	s_or_b64 exec, exec, s[0:1]
	v_mov_b32_e32 v2, s29
	s_waitcnt lgkmcnt(0)
	s_barrier
	ds_read_b32 v2, v2
	s_movk_i32 s0, 0x1ff
	s_waitcnt lgkmcnt(0)
	v_cmp_lt_u32_e32 vcc, s0, v2
	v_readfirstlane_b32 s3, v2
	s_mov_b64 s[0:1], -1
	s_cbranch_vccnz .LBB0_1244
	s_lshl_b32 s0, s3, 1
	s_and_b32 s34, s3, 0x1fc
	s_and_b32 s0, s0, 6
	s_or_b32 s2, s34, s27
	s_add_i32 s33, s0, s16
	s_mul_i32 s0, s2, 0x3c00
	s_add_u32 s14, s88, s0
	s_addc_u32 s15, s89, 0
	s_lshl_b32 s22, s33, 6
	s_lshl_b64 s[0:1], s[22:23], 2
	s_add_u32 s14, s14, s0
	s_addc_u32 s15, s15, s1
	v_lshlrev_b32_e32 v156, 1, v154
	s_mulk_i32 s34, 0x3c00
	global_load_dwordx4 v[54:57], v156, s[14:15] offset:128
	global_load_dwordx4 v[62:65], v156, s[14:15]
	s_add_u32 s14, s88, s34
	s_addc_u32 s15, s89, 0
	s_add_u32 s0, s14, s0
	s_addc_u32 s1, s15, s1
	s_lshl_b32 s3, s3, 12
	s_and_b32 s3, s3, 0x1fc000
	s_add_i32 s3, s33, s3
	s_lshl_b32 s14, s3, 6
	s_mov_b32 s15, s23
	s_lshl_b64 s[14:15], s[14:15], 2
	v_lshl_add_u64 v[2:3], s[0:1], 0, v[156:157]
	v_lshl_add_u64 v[194:195], v[158:159], 0, s[14:15]
	v_lshl_add_u64 v[198:199], v[2:3], 0, s[30:31]
	v_lshl_add_u64 v[2:3], v[194:195], 0, v[162:163]
	v_lshl_add_u64 v[4:5], v[198:199], 0, v[164:165]
	v_lshl_add_u64 v[200:201], v[160:161], 0, s[14:15]
	v_cndmask_b32_e64 v3, v3, v5, s[6:7]
	v_cndmask_b32_e64 v2, v2, v4, s[6:7]
	v_lshl_add_u64 v[4:5], v[2:3], 0, s[38:39]
	v_lshl_add_u64 v[6:7], v[200:201], 0, v[186:187]
	v_cndmask_b32_e64 v5, v7, v5, s[6:7]
	v_cndmask_b32_e64 v4, v6, v4, s[6:7]
	global_load_dwordx4 v[14:17], v[2:3], off
	global_load_dwordx4 v[10:13], v[2:3], off offset:128
	global_load_dwordx4 v[34:37], v[4:5], off offset:128
	global_load_dwordx4 v[42:45], v[4:5], off
	v_lshl_add_u64 v[2:3], v[198:199], 0, v[170:171]
	v_lshl_add_u64 v[4:5], v[194:195], 0, v[168:169]
	v_cndmask_b32_e64 v3, v5, v3, s[8:9]
	v_cndmask_b32_e64 v2, v4, v2, s[8:9]
	v_lshl_add_u64 v[4:5], v[2:3], 0, s[38:39]
	v_lshl_add_u64 v[6:7], v[200:201], 0, v[188:189]
	v_cndmask_b32_e64 v5, v7, v5, s[8:9]
	v_cndmask_b32_e64 v4, v6, v4, s[8:9]
	global_load_dwordx4 v[22:25], v[2:3], off
	global_load_dwordx4 v[18:21], v[2:3], off offset:128
	global_load_dwordx4 v[38:41], v[4:5], off offset:128
	global_load_dwordx4 v[50:53], v[4:5], off
	v_lshl_add_u64 v[2:3], v[198:199], 0, v[176:177]
	v_lshl_add_u64 v[4:5], v[194:195], 0, v[174:175]
	v_cndmask_b32_e64 v3, v5, v3, s[10:11]
	v_cndmask_b32_e64 v2, v4, v2, s[10:11]
	v_lshl_add_u64 v[4:5], v[2:3], 0, s[38:39]
	v_lshl_add_u64 v[6:7], v[200:201], 0, v[190:191]
	s_mul_i32 s34, s33, 0x188
	s_mov_b32 s35, s23
	v_cndmask_b32_e64 v5, v7, v5, s[10:11]
	v_cndmask_b32_e64 v4, v6, v4, s[10:11]
	s_lshl_b64 s[0:1], s[34:35], 2
	v_readlane_b32 s14, v245, 37
	global_load_dwordx4 v[30:33], v[2:3], off
	global_load_dwordx4 v[26:29], v[2:3], off offset:128
	global_load_dwordx4 v[46:49], v[4:5], off offset:128
	global_load_dwordx4 v[58:61], v[4:5], off
	v_lshl_add_u64 v[2:3], v[198:199], 0, v[182:183]
	v_lshl_add_u64 v[4:5], v[194:195], 0, v[180:181]
	v_readlane_b32 s15, v245, 38
	s_add_u32 s40, s14, s0
	v_cndmask_b32_e64 v3, v5, v3, s[12:13]
	v_cndmask_b32_e64 v2, v4, v2, s[12:13]
	s_addc_u32 s41, s15, s1
	v_lshl_add_u64 v[4:5], v[2:3], 0, s[38:39]
	v_lshl_add_u64 v[6:7], v[200:201], 0, v[192:193]
	v_lshl_add_u64 v[66:67], v[166:167], 2, s[40:41]
	v_cndmask_b32_e64 v7, v7, v5, s[12:13]
	v_cndmask_b32_e64 v6, v6, v4, s[12:13]
	v_lshl_add_u64 v[68:69], v[172:173], 2, s[40:41]
	v_lshl_add_u64 v[78:79], v[178:179], 2, s[40:41]
	global_load_dwordx4 v[74:77], v[2:3], off
	global_load_dwordx4 v[70:73], v[2:3], off offset:128
	s_nop 0
	global_load_dwordx4 v[2:5], v[6:7], off offset:128
	s_nop 0
	global_load_dwordx4 v[6:9], v[6:7], off
	v_lshl_add_u64 v[80:81], v[184:185], 2, s[40:41]
	global_load_dword v228, v[66:67], off
	global_load_dword v227, v[68:69], off
	global_load_dword v226, v[78:79], off
	global_load_dword v222, v[80:81], off
	v_mov_b32_e32 v224, 0
	v_mov_b32_e32 v225, 0xff800000
	s_mov_b32 s3, -8
	v_mov_b32_e32 v223, v155
	v_mov_b32_e32 v220, 0
	v_mov_b32_e32 v221, v224
	v_mov_b32_e32 v218, 0
	v_mov_b32_e32 v219, v224
	v_mov_b32_e32 v214, 0
	v_mov_b32_e32 v215, v224
	v_mov_b32_e32 v216, 0
	v_mov_b32_e32 v217, v224
	s_waitcnt vmcnt(0)
	v_pk_mul_f32 v[204:205], v[56:57], s[28:29] op_sel_hi:[1,0]
	v_pk_mul_f32 v[208:209], v[64:65], s[28:29] op_sel_hi:[1,0]
	v_pk_mul_f32 v[206:207], v[62:63], s[28:29] op_sel_hi:[1,0]
	v_pk_mul_f32 v[202:203], v[54:55], s[28:29] op_sel_hi:[1,0]
	v_pk_mov_b32 v[210:211], v[206:207], v[208:209] op_sel:[1,0]
	v_mov_b32_e32 v212, v206
	v_mov_b32_e32 v213, v209
; __device__ __forceinline__ void p_attn_sample(const float* P, const float* ck, const float* cv, const float* relb, bf16* heads, const float* sbt, unsigned* qctr, volatile LAS unsigned* slot, int wave, int lane_in) {
;     ...
;         SLOADB(ak0, ak1, av0, av1, ab, 0)
; #pragma unroll 1
;         for (int it0 = 0; it0 < 48; it0 += 8) {
;             SLOADB(bk0, bk1, bv0, bv1, bbv, it0 + 4)
.LBB0_1251:
	v_subrev_u32_e32 v255, 56, v223
	v_min_i32_e32 v255, 0x187, v255
	v_lshl_add_u32 v255, v255, 2, s101
	ds_read_b32 v246, v255
	v_subrev_u32_e32 v255, 48, v223
	v_min_i32_e32 v255, 0x187, v255
	v_lshl_add_u32 v255, v255, 2, s101
	ds_read_b32 v247, v255
	v_subrev_u32_e32 v255, 40, v223
	v_min_i32_e32 v255, 0x187, v255
	v_lshl_add_u32 v255, v255, 2, s101
	ds_read_b32 v248, v255
	v_subrev_u32_e32 v255, 32, v223
	v_min_i32_e32 v255, 0x187, v255
	v_lshl_add_u32 v255, v255, 2, s101
	ds_read_b32 v249, v255
	v_subrev_u32_e32 v255, 24, v223
	v_min_i32_e32 v255, 0x187, v255
	v_lshl_add_u32 v255, v255, 2, s101
	ds_read_b32 v250, v255
	v_subrev_u32_e32 v255, 16, v223
	v_min_i32_e32 v255, 0x187, v255
	v_lshl_add_u32 v255, v255, 2, s101
	ds_read_b32 v251, v255
	v_subrev_u32_e32 v255, 8, v223
	v_min_i32_e32 v255, 0x187, v255
	v_lshl_add_u32 v255, v255, 2, s101
	ds_read_b32 v252, v255
	v_min_i32_e32 v255, 0x187, v223
	v_lshl_add_u32 v255, v255, 2, s101
	ds_read_b32 v253, v255
	s_waitcnt lgkmcnt(0)
	v_subrev_u32_e32 v66, 56, v223
	v_mov_b32_e32 v66, v246
	v_cmp_lt_i32_e32 vcc, s19, v66
	v_min_i32_e32 v54, 0x182, v66
	s_nop 0
	v_cndmask_b32_e64 v55, 0, 1, vcc
	v_cmp_gt_i32_e32 vcc, s24, v66
	s_nop 1
	v_cndmask_b32_e32 v55, 2, v55, vcc
	v_mul_i32_i24_e32 v56, 0xffffff7f, v55
	v_lshlrev_b32_e32 v55, 1, v55
	v_add_lshl_u32 v54, v56, v54, v55
	v_sub_u32_e32 v156, s18, v54
	v_cmp_lt_i32_e32 vcc, s25, v156
	v_cmp_gt_i32_e64 s[0:1], s17, v156
	s_and_saveexec_b64 s[14:15], s[0:1]
	s_xor_b64 s[0:1], exec, s[14:15]
	v_ashrrev_i32_e32 v55, 31, v156
	v_mov_b32_e32 v54, v156
	v_lshlrev_b64 v[56:57], 11, v[54:55]
	v_lshl_add_u64 v[54:55], v[194:195], 0, v[56:57]
	s_andn2_saveexec_b64 s[0:1], s[0:1]
	v_add_u32_e32 v54, 0xfffff800, v156
	v_mad_u64_u32 v[54:55], s[14:15], v54, s26, v[198:199]
	v_lshlrev_b64 v[56:57], 11, v[156:157]
	s_or_b64 exec, exec, s[0:1]
	v_lshl_add_u64 v[62:63], v[54:55], 0, s[38:39]
	v_lshl_add_u64 v[56:57], v[200:201], 0, v[56:57]
	v_cndmask_b32_e32 v63, v57, v63, vcc
	v_cndmask_b32_e32 v62, v56, v62, vcc
	v_min_i32_e32 v66, 0x187, v66
	global_load_dwordx4 v[102:105], v[54:55], off offset:128
	global_load_dwordx4 v[114:117], v[54:55], off
	s_nop 0
	global_load_dwordx4 v[54:57], v[62:63], off offset:128
	s_nop 0
	global_load_dwordx4 v[62:65], v[62:63], off
	v_ashrrev_i32_e32 v67, 31, v66
	v_lshl_add_u64 v[66:67], v[66:67], 2, s[40:41]
	global_load_dword v229, v[66:67], off
	v_subrev_u32_e32 v82, 48, v223
	v_mov_b32_e32 v82, v247
	v_cmp_lt_i32_e32 vcc, s19, v82
	v_min_i32_e32 v66, 0x182, v82
	s_nop 0
	v_cndmask_b32_e64 v67, 0, 1, vcc
	v_cmp_gt_i32_e32 vcc, s24, v82
	s_nop 1
	v_cndmask_b32_e32 v67, 2, v67, vcc
	v_mul_i32_i24_e32 v68, 0xffffff7f, v67
	v_lshlrev_b32_e32 v67, 1, v67
	v_add_lshl_u32 v66, v68, v66, v67
	v_sub_u32_e32 v68, s18, v66
	v_cmp_lt_i32_e32 vcc, s25, v68
	v_cmp_gt_i32_e64 s[0:1], s17, v68
	s_and_saveexec_b64 s[14:15], s[0:1]
	s_xor_b64 s[0:1], exec, s[14:15]
	v_ashrrev_i32_e32 v69, 31, v68
	v_lshlrev_b64 v[78:79], 11, v[68:69]
	v_lshl_add_u64 v[66:67], v[194:195], 0, v[78:79]
	s_andn2_saveexec_b64 s[0:1], s[0:1]
	v_add_u32_e32 v66, 0xfffff800, v68
	v_mov_b32_e32 v69, v157
	v_mad_u64_u32 v[66:67], s[14:15], v66, s26, v[198:199]
	v_lshlrev_b64 v[78:79], 11, v[68:69]
	s_or_b64 exec, exec, s[0:1]
	v_lshl_add_u64 v[68:69], v[66:67], 0, s[38:39]
	v_lshl_add_u64 v[78:79], v[200:201], 0, v[78:79]
	v_cndmask_b32_e32 v79, v79, v69, vcc
	v_cndmask_b32_e32 v78, v78, v68, vcc
	v_min_i32_e32 v82, 0x187, v82
	global_load_dwordx4 v[118:121], v[66:67], off offset:128
	global_load_dwordx4 v[122:125], v[66:67], off
	s_nop 0
	global_load_dwordx4 v[66:69], v[78:79], off offset:128
	s_nop 0
	global_load_dwordx4 v[78:81], v[78:79], off
	v_ashrrev_i32_e32 v83, 31, v82
	v_lshl_add_u64 v[82:83], v[82:83], 2, s[40:41]
	global_load_dword v230, v[82:83], off
	v_subrev_u32_e32 v90, 40, v223
	v_mov_b32_e32 v90, v248
	v_cmp_lt_i32_e32 vcc, s19, v90
	v_min_i32_e32 v82, 0x182, v90
	s_nop 0
	v_cndmask_b32_e64 v83, 0, 1, vcc
	v_cmp_gt_i32_e32 vcc, s24, v90
	s_nop 1
	v_cndmask_b32_e32 v83, 2, v83, vcc
	v_mul_i32_i24_e32 v84, 0xffffff7f, v83
	v_lshlrev_b32_e32 v83, 1, v83
	v_add_lshl_u32 v82, v84, v82, v83
	v_sub_u32_e32 v84, s18, v82
	v_cmp_lt_i32_e32 vcc, s25, v84
	v_cmp_gt_i32_e64 s[0:1], s17, v84
	s_and_saveexec_b64 s[14:15], s[0:1]
	s_xor_b64 s[0:1], exec, s[14:15]
	v_ashrrev_i32_e32 v85, 31, v84
	v_lshlrev_b64 v[86:87], 11, v[84:85]
	v_lshl_add_u64 v[82:83], v[194:195], 0, v[86:87]
	s_andn2_saveexec_b64 s[0:1], s[0:1]
	v_add_u32_e32 v82, 0xfffff800, v84
	v_mov_b32_e32 v85, v157
	v_mad_u64_u32 v[82:83], s[14:15], v82, s26, v[198:199]
	v_lshlrev_b64 v[86:87], 11, v[84:85]
	s_or_b64 exec, exec, s[0:1]
	v_lshl_add_u64 v[84:85], v[82:83], 0, s[38:39]
	v_lshl_add_u64 v[86:87], v[200:201], 0, v[86:87]
	v_cndmask_b32_e32 v85, v87, v85, vcc
	v_cndmask_b32_e32 v84, v86, v84, vcc
	global_load_dwordx4 v[134:137], v[82:83], off offset:128
	global_load_dwordx4 v[138:141], v[82:83], off
	global_load_dwordx4 v[86:89], v[84:85], off offset:128
	global_load_dwordx4 v[94:97], v[84:85], off
	v_min_i32_e32 v82, 0x187, v90
	v_ashrrev_i32_e32 v83, 31, v82
	v_lshl_add_u64 v[82:83], v[82:83], 2, s[40:41]
	global_load_dword v231, v[82:83], off
	v_subrev_u32_e32 v92, 32, v223
	v_mov_b32_e32 v92, v249
	v_cmp_lt_i32_e32 vcc, s19, v92
	v_min_i32_e32 v82, 0x182, v92
	s_nop 0
	v_cndmask_b32_e64 v83, 0, 1, vcc
	v_cmp_gt_i32_e32 vcc, s24, v92
	s_nop 1
	v_cndmask_b32_e32 v83, 2, v83, vcc
	v_mul_i32_i24_e32 v84, 0xffffff7f, v83
	v_lshlrev_b32_e32 v83, 1, v83
	v_add_lshl_u32 v82, v84, v82, v83
	v_sub_u32_e32 v84, s18, v82
	v_cmp_lt_i32_e32 vcc, s25, v84
	v_cmp_gt_i32_e64 s[0:1], s17, v84
; __device__ __forceinline__ void p_attn_sample(const float* P, const float* ck, const float* cv, const float* relb, bf16* heads, const float* sbt, unsigned* qctr, volatile LAS unsigned* slot, int wave, int lane_in) {
;     ...
;         SLOADB(ak0, ak1, av0, av1, ab, 0)
; #pragma unroll 1
;         for (int it0 = 0; it0 < 48; it0 += 8) {
;             SLOADB(bk0, bk1, bv0, bv1, bbv, it0 + 4)
;             SPROCB(ak0, ak1, av0, av1, ab)
;             SLOADB(ak0, ak1, av0, av1, ab, it0 + 8)
;             SPROCB(bk0, bk1, bv0, bv1, bbv)
	s_and_saveexec_b64 s[14:15], s[0:1]
	s_xor_b64 s[0:1], exec, s[14:15]
	v_ashrrev_i32_e32 v85, 31, v84
	v_lshlrev_b64 v[90:91], 11, v[84:85]
	v_lshl_add_u64 v[82:83], v[194:195], 0, v[90:91]
	s_andn2_saveexec_b64 s[0:1], s[0:1]
	v_add_u32_e32 v82, 0xfffff800, v84
	v_mov_b32_e32 v85, v157
	v_mad_u64_u32 v[82:83], s[14:15], v82, s26, v[198:199]
	v_lshlrev_b64 v[90:91], 11, v[84:85]
	s_or_b64 exec, exec, s[0:1]
	v_lshl_add_u64 v[84:85], v[82:83], 0, s[38:39]
	v_lshl_add_u64 v[90:91], v[200:201], 0, v[90:91]
	v_cndmask_b32_e32 v85, v91, v85, vcc
	v_cndmask_b32_e32 v84, v90, v84, vcc
	global_load_dwordx4 v[142:145], v[82:83], off offset:128
	global_load_dwordx4 v[146:149], v[82:83], off
	global_load_dwordx4 v[110:113], v[84:85], off offset:128
	global_load_dwordx4 v[126:129], v[84:85], off
	v_min_i32_e32 v82, 0x187, v92
	v_ashrrev_i32_e32 v83, 31, v82
	v_lshl_add_u64 v[82:83], v[82:83], 2, s[40:41]
	global_load_dword v232, v[82:83], off
	v_mov_b32_e32 v82, v15
	v_mov_b32_e32 v15, v17
	v_mov_b32_e32 v83, v16
	v_pk_mul_f32 v[14:15], v[212:213], v[14:15]
	v_pk_mul_f32 v[12:13], v[204:205], v[12:13]
	v_pk_mul_f32 v[10:11], v[202:203], v[10:11]
	v_pk_fma_f32 v[14:15], v[210:211], v[82:83], v[14:15]
	v_mov_b32_e32 v16, v12
	v_mov_b32_e32 v17, v10
	v_mov_b32_e32 v10, v13
	v_pk_add_f32 v[10:11], v[16:17], v[10:11]
	v_add_f32_e32 v12, v14, v15
	v_add_f32_e32 v11, v11, v12
	v_add_f32_e32 v10, v10, v11
	v_mov_b32_e32 v11, v24
	v_pk_mul_f32 v[14:15], v[202:203], v[18:19]
	v_add_f32_dpp v10, v10, v10 quad_perm:[1,0,3,2] row_mask:0xf bank_mask:0xf bound_ctrl:1
	v_mov_b32_e32 v17, v14
	v_subrev_u32_e32 v18, 24, v223
	v_mov_b32_e32 v18, v250
	v_add_f32_dpp v236, v10, v10 quad_perm:[2,3,0,1] row_mask:0xf bank_mask:0xf bound_ctrl:1
	v_mov_b32_e32 v10, v23
	v_mov_b32_e32 v23, v25
	v_pk_mul_f32 v[12:13], v[212:213], v[22:23]
	v_cmp_lt_i32_e32 vcc, s19, v18
	v_pk_fma_f32 v[10:11], v[210:211], v[10:11], v[12:13]
	v_pk_mul_f32 v[12:13], v[204:205], v[20:21]
	v_add_f32_e32 v10, v10, v11
	v_mov_b32_e32 v16, v12
	v_mov_b32_e32 v14, v13
	v_pk_add_f32 v[12:13], v[16:17], v[14:15]
	v_mov_b32_e32 v11, v32
	v_add_f32_e32 v10, v13, v10
	v_add_f32_e32 v10, v12, v10
	v_pk_mul_f32 v[14:15], v[202:203], v[26:27]
	v_mov_b32_e32 v237, 0
	v_add_f32_dpp v10, v10, v10 quad_perm:[1,0,3,2] row_mask:0xf bank_mask:0xf bound_ctrl:1
	v_mov_b32_e32 v17, v14
	v_mov_b32_e32 v239, 0
	v_add_f32_dpp v238, v10, v10 quad_perm:[2,3,0,1] row_mask:0xf bank_mask:0xf bound_ctrl:1
	v_mov_b32_e32 v10, v31
	v_mov_b32_e32 v31, v33
	v_pk_mul_f32 v[12:13], v[212:213], v[30:31]
	v_mov_b32_e32 v241, 0
	v_pk_fma_f32 v[10:11], v[210:211], v[10:11], v[12:13]
	v_pk_mul_f32 v[12:13], v[204:205], v[28:29]
	v_add_f32_e32 v10, v10, v11
	v_mov_b32_e32 v16, v12
	v_mov_b32_e32 v14, v13
	v_pk_add_f32 v[12:13], v[16:17], v[14:15]
	s_waitcnt vmcnt(23)
	v_mov_b32_e32 v11, v76
	v_add_f32_e32 v10, v13, v10
	v_add_f32_e32 v10, v12, v10
	v_pk_mul_f32 v[14:15], v[202:203], v[70:71]
	v_mov_b32_dpp v237, v236 row_half_mirror row_mask:0xf bank_mask:0xf
	v_add_f32_dpp v10, v10, v10 quad_perm:[1,0,3,2] row_mask:0xf bank_mask:0xf bound_ctrl:1
	v_mov_b32_e32 v17, v14
	v_mov_b32_dpp v239, v238 row_half_mirror row_mask:0xf bank_mask:0xf
	v_add_f32_dpp v240, v10, v10 quad_perm:[2,3,0,1] row_mask:0xf bank_mask:0xf bound_ctrl:1
	v_mov_b32_e32 v10, v75
	v_mov_b32_e32 v75, v77
	v_pk_mul_f32 v[12:13], v[212:213], v[74:75]
	v_mov_b32_e32 v77, 0
	v_pk_fma_f32 v[10:11], v[210:211], v[10:11], v[12:13]
	v_pk_mul_f32 v[12:13], v[204:205], v[72:73]
	v_add_f32_e32 v10, v10, v11
	v_mov_b32_e32 v16, v12
	v_mov_b32_e32 v14, v13
	v_pk_add_f32 v[12:13], v[16:17], v[14:15]
	v_cndmask_b32_e64 v11, 0, 1, vcc
	v_add_f32_e32 v10, v13, v10
	v_add_f32_e32 v10, v12, v10
	v_cmp_gt_i32_e32 vcc, s24, v18
	v_mov_b32_dpp v241, v240 row_half_mirror row_mask:0xf bank_mask:0xf
	v_add_f32_dpp v10, v10, v10 quad_perm:[1,0,3,2] row_mask:0xf bank_mask:0xf bound_ctrl:1
	v_cndmask_b32_e32 v11, 2, v11, vcc
	v_mul_i32_i24_e32 v12, 0xffffff7f, v11
	v_add_f32_dpp v76, v10, v10 quad_perm:[2,3,0,1] row_mask:0xf bank_mask:0xf bound_ctrl:1
	v_min_i32_e32 v10, 0x182, v18
	v_lshlrev_b32_e32 v11, 1, v11
	v_add_lshl_u32 v10, v12, v10, v11
	v_sub_u32_e32 v156, s18, v10
	v_mov_b32_dpp v77, v76 row_half_mirror row_mask:0xf bank_mask:0xf
	v_cmp_lt_i32_e32 vcc, s25, v156
	v_cmp_gt_i32_e64 s[0:1], s17, v156
	s_and_saveexec_b64 s[14:15], s[0:1]
	s_xor_b64 s[0:1], exec, s[14:15]
	v_ashrrev_i32_e32 v11, 31, v156
	v_mov_b32_e32 v10, v156
	v_lshlrev_b64 v[10:11], 11, v[10:11]
	v_lshl_add_u64 v[14:15], v[194:195], 0, v[10:11]
	s_andn2_saveexec_b64 s[0:1], s[0:1]
	v_add_u32_e32 v10, 0xfffff800, v156
	v_mad_u64_u32 v[14:15], s[14:15], v10, s26, v[198:199]
	v_lshlrev_b64 v[10:11], 11, v[156:157]
	s_or_b64 exec, exec, s[0:1]
	v_lshl_add_u64 v[12:13], v[14:15], 0, s[38:39]
	v_lshl_add_u64 v[10:11], v[200:201], 0, v[10:11]
	v_min_i32_e32 v18, 0x187, v18
	v_cndmask_b32_e32 v21, v11, v13, vcc
	v_cndmask_b32_e32 v20, v10, v12, vcc
	global_load_dwordx4 v[10:13], v[14:15], off offset:128
	s_nop 0
	global_load_dwordx4 v[14:17], v[14:15], off
	s_nop 0
	global_load_dwordx4 v[90:93], v[20:21], off offset:128
	global_load_dwordx4 v[150:153], v[20:21], off
	v_ashrrev_i32_e32 v19, 31, v18
	v_lshl_add_u64 v[18:19], v[18:19], 2, s[40:41]
	global_load_dword v233, v[18:19], off
	v_add_u32_e32 v26, -16, v223
	v_mov_b32_e32 v26, v251
	v_cmp_lt_i32_e32 vcc, s19, v26
	v_min_i32_e32 v18, 0x182, v26
	s_nop 0
	v_cndmask_b32_e64 v19, 0, 1, vcc
	v_cmp_gt_i32_e32 vcc, s24, v26
	s_nop 1
	v_cndmask_b32_e32 v19, 2, v19, vcc
	v_mul_i32_i24_e32 v20, 0xffffff7f, v19
	v_lshlrev_b32_e32 v19, 1, v19
	v_add_lshl_u32 v18, v20, v18, v19
; __device__ __forceinline__ void p_attn_sample(const float* P, const float* ck, const float* cv, const float* relb, bf16* heads, const float* sbt, unsigned* qctr, volatile LAS unsigned* slot, int wave, int lane_in) {
;     ...
;         SLOADB(ak0, ak1, av0, av1, ab, 0)
; #pragma unroll 1
;         for (int it0 = 0; it0 < 48; it0 += 8) {
;             SLOADB(bk0, bk1, bv0, bv1, bbv, it0 + 4)
;             SPROCB(ak0, ak1, av0, av1, ab)
;             SLOADB(ak0, ak1, av0, av1, ab, it0 + 8)
;             SPROCB(bk0, bk1, bv0, bv1, bbv)
	v_sub_u32_e32 v18, s18, v18
	v_cmp_lt_i32_e32 vcc, s25, v18
	v_cmp_gt_i32_e64 s[0:1], s17, v18
	s_and_saveexec_b64 s[14:15], s[0:1]
	s_xor_b64 s[0:1], exec, s[14:15]
	v_ashrrev_i32_e32 v19, 31, v18
	v_lshlrev_b64 v[20:21], 11, v[18:19]
	v_lshl_add_u64 v[22:23], v[194:195], 0, v[20:21]
	s_andn2_saveexec_b64 s[0:1], s[0:1]
	v_add_u32_e32 v19, 0xfffff800, v18
	v_mad_u64_u32 v[22:23], s[14:15], v19, s26, v[198:199]
	v_mov_b32_e32 v19, v157
	v_lshlrev_b64 v[20:21], 11, v[18:19]
	s_or_b64 exec, exec, s[0:1]
	v_lshl_add_u64 v[18:19], v[22:23], 0, s[38:39]
	v_lshl_add_u64 v[20:21], v[200:201], 0, v[20:21]
	v_min_i32_e32 v26, 0x187, v26
	v_cndmask_b32_e32 v29, v21, v19, vcc
	v_cndmask_b32_e32 v28, v20, v18, vcc
	global_load_dwordx4 v[18:21], v[22:23], off offset:128
	s_nop 0
	global_load_dwordx4 v[22:25], v[22:23], off
	s_nop 0
	global_load_dwordx4 v[82:85], v[28:29], off offset:128
	global_load_dwordx4 v[98:101], v[28:29], off
	v_ashrrev_i32_e32 v27, 31, v26
	v_lshl_add_u64 v[26:27], v[26:27], 2, s[40:41]
	global_load_dword v234, v[26:27], off
	v_add_u32_e32 v70, -8, v223
	v_mov_b32_e32 v70, v252
	v_cmp_lt_i32_e32 vcc, s19, v70
	v_min_i32_e32 v26, 0x182, v70
	s_nop 0
	v_cndmask_b32_e64 v27, 0, 1, vcc
	v_cmp_gt_i32_e32 vcc, s24, v70
	s_nop 1
	v_cndmask_b32_e32 v27, 2, v27, vcc
	v_mul_i32_i24_e32 v28, 0xffffff7f, v27
	v_lshlrev_b32_e32 v27, 1, v27
	v_add_lshl_u32 v26, v28, v26, v27
	v_sub_u32_e32 v26, s18, v26
	v_cmp_lt_i32_e32 vcc, s25, v26
	v_cmp_gt_i32_e64 s[0:1], s17, v26
	s_and_saveexec_b64 s[14:15], s[0:1]
	s_xor_b64 s[0:1], exec, s[14:15]
	v_ashrrev_i32_e32 v27, 31, v26
	v_lshlrev_b64 v[28:29], 11, v[26:27]
	v_lshl_add_u64 v[30:31], v[194:195], 0, v[28:29]
	s_andn2_saveexec_b64 s[0:1], s[0:1]
	v_add_u32_e32 v27, 0xfffff800, v26
	v_mad_u64_u32 v[30:31], s[14:15], v27, s26, v[198:199]
	v_mov_b32_e32 v27, v157
	v_lshlrev_b64 v[28:29], 11, v[26:27]
	s_or_b64 exec, exec, s[0:1]
	v_lshl_add_u64 v[26:27], v[30:31], 0, s[38:39]
	v_lshl_add_u64 v[28:29], v[200:201], 0, v[28:29]
	v_min_i32_e32 v70, 0x187, v70
	v_cndmask_b32_e32 v73, v29, v27, vcc
	v_cndmask_b32_e32 v72, v28, v26, vcc
	global_load_dwordx4 v[26:29], v[30:31], off offset:128
	s_nop 0
	global_load_dwordx4 v[30:33], v[30:31], off
	s_nop 0
	global_load_dwordx4 v[106:109], v[72:73], off offset:128
	global_load_dwordx4 v[130:133], v[72:73], off
	v_ashrrev_i32_e32 v71, 31, v70
	v_lshl_add_u64 v[70:71], v[70:71], 2, s[40:41]
	global_load_dword v235, v[70:71], off
	v_mov_b32_e32 v254, v253
	v_cmp_lt_i32_e32 vcc, s19, v254
	v_min_i32_e32 v70, 0x182, v254
	s_nop 0
	v_cndmask_b32_e64 v71, 0, 1, vcc
	v_cmp_gt_i32_e32 vcc, s24, v254
	s_nop 1
	v_cndmask_b32_e32 v71, 2, v71, vcc
	v_mul_i32_i24_e32 v72, 0xffffff7f, v71
	v_lshlrev_b32_e32 v71, 1, v71
	v_add_lshl_u32 v70, v72, v70, v71
	v_sub_u32_e32 v72, s18, v70
	v_cmp_lt_i32_e32 vcc, s25, v72
	v_cmp_gt_i32_e64 s[0:1], s17, v72
	s_and_saveexec_b64 s[14:15], s[0:1]
	s_xor_b64 s[0:1], exec, s[14:15]
	v_ashrrev_i32_e32 v73, 31, v72
	v_lshlrev_b64 v[70:71], 11, v[72:73]
	v_lshl_add_u64 v[74:75], v[194:195], 0, v[70:71]
	s_andn2_saveexec_b64 s[0:1], s[0:1]
	v_add_u32_e32 v70, 0xfffff800, v72
	v_mov_b32_e32 v73, v157
	v_mad_u64_u32 v[74:75], s[14:15], v70, s26, v[198:199]
	v_lshlrev_b64 v[70:71], 11, v[72:73]
	s_or_b64 exec, exec, s[0:1]
	v_add_f32_e32 v72, v236, v237
	v_add_f32_e32 v73, v228, v72
	v_max_f32_e32 v72, v225, v225
	v_max_f32_e32 v156, v72, v73
	v_sub_f32_e32 v73, v73, v156
	v_mul_f32_e32 v73, 0x3fb8aa3b, v73
	v_exp_f32_e32 v228, v73
	v_add_f32_e32 v73, v238, v239
	v_add_f32_e32 v73, v227, v73
	v_sub_f32_e32 v72, v225, v156
	v_max_f32_e32 v225, v156, v73
	v_sub_f32_e32 v73, v73, v225
	v_mul_f32_e32 v73, 0x3fb8aa3b, v73
	v_sub_f32_e32 v156, v156, v225
	v_exp_f32_e32 v238, v73
	v_add_f32_e32 v73, v240, v241
	v_mul_f32_e32 v156, 0x3fb8aa3b, v156
	v_add_f32_e32 v73, v226, v73
	v_mul_f32_e32 v72, 0x3fb8aa3b, v72
	v_exp_f32_e32 v236, v156
	v_max_f32_e32 v156, v225, v73
	v_exp_f32_e32 v72, v72
	v_sub_f32_e32 v225, v225, v156
	v_sub_f32_e32 v73, v73, v156
	v_mul_f32_e32 v225, 0x3fb8aa3b, v225
	v_mul_f32_e32 v73, 0x3fb8aa3b, v73
	v_exp_f32_e32 v226, v225
	v_exp_f32_e32 v240, v73
	v_fma_f32 v73, v224, v72, v228
	v_fma_f32 v73, v73, v236, v238
	s_waitcnt vmcnt(30)
	v_pk_mul_f32 v[42:43], v[42:43], v[228:229] op_sel_hi:[1,0]
	v_fma_f32 v225, v73, v226, v240
	v_add_f32_e32 v73, v76, v77
	v_add_f32_e32 v73, v222, v73
	v_max_f32_e32 v227, v156, v73
	v_sub_f32_e32 v73, v73, v227
	v_sub_f32_e32 v76, v156, v227
	v_mul_f32_e32 v73, 0x3fb8aa3b, v73
	v_mul_f32_e32 v76, 0x3fb8aa3b, v76
	v_exp_f32_e32 v156, v73
	v_exp_f32_e32 v224, v76
	v_pk_fma_f32 v[42:43], v[220:221], v[72:73], v[42:43] op_sel_hi:[1,0,1]
	v_pk_mul_f32 v[50:51], v[50:51], v[238:239] op_sel_hi:[1,0]
	v_pk_mul_f32 v[6:7], v[6:7], v[156:157] op_sel_hi:[1,0]
	v_pk_fma_f32 v[42:43], v[42:43], v[236:237], v[50:51] op_sel_hi:[1,0,1]
	v_pk_mul_f32 v[50:51], v[58:59], v[240:241] op_sel_hi:[1,0]
	v_pk_mul_f32 v[8:9], v[8:9], v[156:157] op_sel_hi:[1,0]
	v_pk_fma_f32 v[42:43], v[42:43], v[226:227], v[50:51] op_sel_hi:[1,0,1]
	v_pk_mul_f32 v[2:3], v[2:3], v[156:157] op_sel_hi:[1,0]
	v_pk_fma_f32 v[42:43], v[42:43], v[224:225], v[6:7] op_sel_hi:[1,0,1]
	v_pk_mul_f32 v[6:7], v[44:45], v[228:229] op_sel_hi:[1,0]
	v_pk_mul_f32 v[44:45], v[52:53], v[238:239] op_sel_hi:[1,0]
	v_pk_fma_f32 v[6:7], v[218:219], v[72:73], v[6:7] op_sel_hi:[1,0,1]
	v_pk_mul_f32 v[4:5], v[4:5], v[156:157] op_sel_hi:[1,0]
	v_pk_fma_f32 v[6:7], v[6:7], v[236:237], v[44:45] op_sel_hi:[1,0,1]
	v_pk_mul_f32 v[44:45], v[60:61], v[240:241] op_sel_hi:[1,0]
	v_fmac_f32_e32 v156, v225, v224
	v_pk_fma_f32 v[6:7], v[6:7], v[226:227], v[44:45] op_sel_hi:[1,0,1]
; __device__ __forceinline__ void p_attn_sample(const float* P, const float* ck, const float* cv, const float* relb, bf16* heads, const float* sbt, unsigned* qctr, volatile LAS unsigned* slot, int wave, int lane_in) {
;     ...
;         SLOADB(ak0, ak1, av0, av1, ab, 0)
; #pragma unroll 1
;         for (int it0 = 0; it0 < 48; it0 += 8) {
;             SLOADB(bk0, bk1, bv0, bv1, bbv, it0 + 4)
;             SPROCB(ak0, ak1, av0, av1, ab)
;             SLOADB(ak0, ak1, av0, av1, ab, it0 + 8)
;             SPROCB(bk0, bk1, bv0, bv1, bbv)
	s_add_i32 s3, s3, 8
	v_pk_fma_f32 v[44:45], v[6:7], v[224:225], v[8:9] op_sel_hi:[1,0,1]
	v_pk_mul_f32 v[6:7], v[34:35], v[228:229] op_sel_hi:[1,0]
	v_pk_mul_f32 v[8:9], v[38:39], v[238:239] op_sel_hi:[1,0]
	v_pk_fma_f32 v[6:7], v[214:215], v[72:73], v[6:7] op_sel_hi:[1,0,1]
	v_min_i32_e32 v38, 0x187, v254
	v_pk_fma_f32 v[6:7], v[6:7], v[236:237], v[8:9] op_sel_hi:[1,0,1]
	v_pk_mul_f32 v[8:9], v[46:47], v[240:241] op_sel_hi:[1,0]
	v_ashrrev_i32_e32 v39, 31, v38
	v_pk_fma_f32 v[6:7], v[6:7], v[226:227], v[8:9] op_sel_hi:[1,0,1]
	v_lshl_add_u64 v[38:39], v[38:39], 2, s[40:41]
	v_pk_fma_f32 v[34:35], v[6:7], v[224:225], v[2:3] op_sel_hi:[1,0,1]
	v_pk_mul_f32 v[2:3], v[36:37], v[228:229] op_sel_hi:[1,0]
	v_pk_mul_f32 v[6:7], v[40:41], v[238:239] op_sel_hi:[1,0]
	v_pk_fma_f32 v[2:3], v[216:217], v[72:73], v[2:3] op_sel_hi:[1,0,1]
	v_pk_mul_f32 v[40:41], v[206:207], v[114:115]
	v_pk_fma_f32 v[2:3], v[2:3], v[236:237], v[6:7] op_sel_hi:[1,0,1]
	v_pk_mul_f32 v[6:7], v[48:49], v[240:241] op_sel_hi:[1,0]
	s_cmp_gt_u32 s3, 39
	v_pk_fma_f32 v[2:3], v[2:3], v[226:227], v[6:7] op_sel_hi:[1,0,1]
	v_add_u32_e32 v223, 64, v223
	v_pk_fma_f32 v[36:37], v[2:3], v[224:225], v[4:5] op_sel_hi:[1,0,1]
	v_lshl_add_u64 v[2:3], v[74:75], 0, s[38:39]
	v_lshl_add_u64 v[4:5], v[200:201], 0, v[70:71]
	v_cndmask_b32_e32 v7, v5, v3, vcc
	v_cndmask_b32_e32 v6, v4, v2, vcc
	global_load_dwordx4 v[70:73], v[74:75], off offset:128
	s_nop 0
	global_load_dwordx4 v[74:77], v[74:75], off
	s_nop 0
	global_load_dwordx4 v[2:5], v[6:7], off offset:128
	s_nop 0
	global_load_dwordx4 v[6:9], v[6:7], off
	s_nop 0
	global_load_dword v222, v[38:39], off
	v_pk_mul_f32 v[38:39], v[208:209], v[116:117]
	s_nop 0
	v_pk_mov_b32 v[46:47], v[40:41], v[38:39] op_sel:[1,0]
	v_mov_b32_e32 v41, v39
	v_pk_add_f32 v[38:39], v[46:47], v[40:41]
	v_pk_mul_f32 v[40:41], v[204:205], v[104:105]
	v_pk_mul_f32 v[46:47], v[202:203], v[102:103]
	v_mov_b32_e32 v48, v40
	v_mov_b32_e32 v49, v46
	v_mov_b32_e32 v46, v41
	v_pk_add_f32 v[40:41], v[48:49], v[46:47]
	v_add_f32_e32 v38, v38, v39
	v_add_f32_e32 v38, v38, v41
	v_add_f32_e32 v38, v40, v38
	s_waitcnt vmcnt(33)
	v_pk_mul_f32 v[46:47], v[208:209], v[124:125]
	v_pk_mul_f32 v[48:49], v[206:207], v[122:123]
	v_add_f32_dpp v38, v38, v38 quad_perm:[1,0,3,2] row_mask:0xf bank_mask:0xf bound_ctrl:1
	v_pk_mov_b32 v[50:51], v[48:49], v[46:47] op_sel:[1,0]
	v_mov_b32_e32 v49, v47
	v_add_f32_dpp v38, v38, v38 quad_perm:[2,3,0,1] row_mask:0xf bank_mask:0xf bound_ctrl:1
	v_pk_add_f32 v[46:47], v[50:51], v[48:49]
	v_pk_mul_f32 v[48:49], v[204:205], v[120:121]
	v_add_f32_dpp v38, v38, v38 row_half_mirror row_mask:0xf bank_mask:0xf bound_ctrl:1
	v_add_f32_e32 v39, v229, v38
	v_max_f32_e32 v41, v227, v39
	v_sub_f32_e32 v39, v39, v41
	v_pk_mul_f32 v[50:51], v[202:203], v[118:119]
	v_mul_f32_e32 v39, 0x3fb8aa3b, v39
	v_mov_b32_e32 v52, v48
	v_mov_b32_e32 v53, v50
	v_mov_b32_e32 v50, v49
	v_exp_f32_e32 v40, v39
	v_pk_add_f32 v[48:49], v[52:53], v[50:51]
	v_add_f32_e32 v39, v46, v47
	v_add_f32_e32 v39, v39, v49
	v_add_f32_e32 v39, v48, v39
	s_waitcnt vmcnt(28)
	v_pk_mul_f32 v[50:51], v[208:209], v[140:141]
	v_pk_mul_f32 v[52:53], v[206:207], v[138:139]
	v_add_f32_dpp v39, v39, v39 quad_perm:[1,0,3,2] row_mask:0xf bank_mask:0xf bound_ctrl:1
	v_pk_mov_b32 v[58:59], v[52:53], v[50:51] op_sel:[1,0]
	v_mov_b32_e32 v53, v51
	v_add_f32_dpp v39, v39, v39 quad_perm:[2,3,0,1] row_mask:0xf bank_mask:0xf bound_ctrl:1
	v_pk_add_f32 v[50:51], v[58:59], v[52:53]
	v_pk_mul_f32 v[52:53], v[204:205], v[136:137]
	v_add_f32_dpp v39, v39, v39 row_half_mirror row_mask:0xf bank_mask:0xf bound_ctrl:1
	v_add_f32_e32 v39, v230, v39
	v_max_f32_e32 v47, v41, v39
	v_sub_f32_e32 v39, v39, v47
	v_pk_mul_f32 v[58:59], v[202:203], v[134:135]
	v_mul_f32_e32 v39, 0x3fb8aa3b, v39
	v_mov_b32_e32 v60, v52
	v_mov_b32_e32 v61, v58
	v_mov_b32_e32 v58, v53
	v_exp_f32_e32 v48, v39
	v_pk_add_f32 v[52:53], v[60:61], v[58:59]
	v_add_f32_e32 v39, v50, v51
	v_add_f32_e32 v39, v39, v53
	v_add_f32_e32 v39, v52, v39
	v_sub_f32_e32 v38, v227, v41
	v_sub_f32_e32 v41, v41, v47
	v_add_f32_dpp v39, v39, v39 quad_perm:[1,0,3,2] row_mask:0xf bank_mask:0xf bound_ctrl:1
	v_mul_f32_e32 v41, 0x3fb8aa3b, v41
	s_waitcnt vmcnt(23)
	v_pk_mul_f32 v[58:59], v[208:209], v[148:149]
	v_add_f32_dpp v39, v39, v39 quad_perm:[2,3,0,1] row_mask:0xf bank_mask:0xf bound_ctrl:1
	v_pk_mul_f32 v[60:61], v[206:207], v[146:147]
	v_exp_f32_e32 v46, v41
	v_add_f32_dpp v39, v39, v39 row_half_mirror row_mask:0xf bank_mask:0xf bound_ctrl:1
	v_add_f32_e32 v39, v231, v39
	v_max_f32_e32 v41, v47, v39
	v_pk_mov_b32 v[102:103], v[60:61], v[58:59] op_sel:[1,0]
	v_mov_b32_e32 v61, v59
	v_sub_f32_e32 v39, v39, v41
	v_pk_add_f32 v[58:59], v[102:103], v[60:61]
	v_pk_mul_f32 v[60:61], v[204:205], v[144:145]
	v_pk_mul_f32 v[102:103], v[202:203], v[142:143]
	v_mul_f32_e32 v39, 0x3fb8aa3b, v39
	v_mov_b32_e32 v104, v60
	v_mov_b32_e32 v105, v102
	v_mov_b32_e32 v102, v61
	v_exp_f32_e32 v52, v39
	v_pk_add_f32 v[60:61], v[104:105], v[102:103]
	v_add_f32_e32 v39, v58, v59
	v_add_f32_e32 v39, v39, v61
	v_add_f32_e32 v39, v60, v39
	v_mul_f32_e32 v38, 0x3fb8aa3b, v38
	v_exp_f32_e32 v38, v38
	v_add_f32_dpp v39, v39, v39 quad_perm:[1,0,3,2] row_mask:0xf bank_mask:0xf bound_ctrl:1
	v_sub_f32_e32 v47, v47, v41
	v_mul_f32_e32 v47, 0x3fb8aa3b, v47
	v_add_f32_dpp v39, v39, v39 quad_perm:[2,3,0,1] row_mask:0xf bank_mask:0xf bound_ctrl:1
	v_exp_f32_e32 v50, v47
	s_nop 0
	v_add_f32_dpp v39, v39, v39 row_half_mirror row_mask:0xf bank_mask:0xf bound_ctrl:1
	s_waitcnt vmcnt(20)
; __device__ __forceinline__ void p_attn_sample(const float* P, const float* ck, const float* cv, const float* relb, bf16* heads, const float* sbt, unsigned* qctr, volatile LAS unsigned* slot, int wave, int lane_in) {
;     ...
;         SLOADB(ak0, ak1, av0, av1, ab, 0)
; #pragma unroll 1
;         for (int it0 = 0; it0 < 48; it0 += 8) {
;             SLOADB(bk0, bk1, bv0, bv1, bbv, it0 + 4)
;             SPROCB(ak0, ak1, av0, av1, ab)
;             SLOADB(ak0, ak1, av0, av1, ab, it0 + 8)
;             SPROCB(bk0, bk1, bv0, bv1, bbv)
;         }
;         SPROCB(ak0, ak1, av0, av1, ab)
	v_add_f32_e32 v39, v232, v39
	v_max_f32_e32 v225, v41, v39
	v_sub_f32_e32 v39, v39, v225
	v_mul_f32_e32 v39, 0x3fb8aa3b, v39
	v_sub_f32_e32 v41, v41, v225
	v_exp_f32_e32 v60, v39
	v_fma_f32 v39, v156, v38, v40
	v_mul_f32_e32 v41, 0x3fb8aa3b, v41
	v_fma_f32 v39, v39, v46, v48
	v_exp_f32_e32 v58, v41
	v_fma_f32 v39, v39, v50, v52
	v_pk_mul_f32 v[62:63], v[62:63], v[40:41] op_sel_hi:[1,0]
	v_fma_f32 v224, v39, v58, v60
	v_pk_fma_f32 v[42:43], v[42:43], v[38:39], v[62:63] op_sel_hi:[1,0,1]
	v_pk_mul_f32 v[62:63], v[78:79], v[48:49] op_sel_hi:[1,0]
	s_nop 0
	v_pk_fma_f32 v[42:43], v[42:43], v[46:47], v[62:63] op_sel_hi:[1,0,1]
	v_pk_mul_f32 v[62:63], v[94:95], v[52:53] op_sel_hi:[1,0]
	s_nop 0
	v_pk_fma_f32 v[42:43], v[42:43], v[50:51], v[62:63] op_sel_hi:[1,0,1]
	v_pk_mul_f32 v[62:63], v[126:127], v[60:61] op_sel_hi:[1,0]
	s_nop 0
	v_pk_fma_f32 v[220:221], v[42:43], v[58:59], v[62:63] op_sel_hi:[1,0,1]
	v_pk_mul_f32 v[42:43], v[64:65], v[40:41] op_sel_hi:[1,0]
	s_nop 0
	v_pk_fma_f32 v[42:43], v[44:45], v[38:39], v[42:43] op_sel_hi:[1,0,1]
	v_pk_mul_f32 v[44:45], v[80:81], v[48:49] op_sel_hi:[1,0]
	s_nop 0
	v_pk_fma_f32 v[42:43], v[42:43], v[46:47], v[44:45] op_sel_hi:[1,0,1]
	v_pk_mul_f32 v[44:45], v[96:97], v[52:53] op_sel_hi:[1,0]
	s_nop 0
	v_pk_fma_f32 v[42:43], v[42:43], v[50:51], v[44:45] op_sel_hi:[1,0,1]
	v_pk_mul_f32 v[44:45], v[128:129], v[60:61] op_sel_hi:[1,0]
	s_nop 0
	v_pk_fma_f32 v[218:219], v[42:43], v[58:59], v[44:45] op_sel_hi:[1,0,1]
	v_pk_mul_f32 v[42:43], v[54:55], v[40:41] op_sel_hi:[1,0]
	s_nop 0
	v_pk_fma_f32 v[34:35], v[34:35], v[38:39], v[42:43] op_sel_hi:[1,0,1]
	v_pk_mul_f32 v[42:43], v[66:67], v[48:49] op_sel_hi:[1,0]
	s_nop 0
	v_pk_fma_f32 v[34:35], v[34:35], v[46:47], v[42:43] op_sel_hi:[1,0,1]
	v_pk_mul_f32 v[42:43], v[86:87], v[52:53] op_sel_hi:[1,0]
	s_nop 0
	v_pk_fma_f32 v[34:35], v[34:35], v[50:51], v[42:43] op_sel_hi:[1,0,1]
	v_pk_mul_f32 v[42:43], v[110:111], v[60:61] op_sel_hi:[1,0]
	s_nop 0
	v_pk_fma_f32 v[214:215], v[34:35], v[58:59], v[42:43] op_sel_hi:[1,0,1]
	v_pk_mul_f32 v[34:35], v[56:57], v[40:41] op_sel_hi:[1,0]
	s_nop 0
	v_pk_fma_f32 v[34:35], v[36:37], v[38:39], v[34:35] op_sel_hi:[1,0,1]
	v_pk_mul_f32 v[36:37], v[68:69], v[48:49] op_sel_hi:[1,0]
	s_nop 0
	v_pk_fma_f32 v[34:35], v[34:35], v[46:47], v[36:37] op_sel_hi:[1,0,1]
	v_pk_mul_f32 v[36:37], v[88:89], v[52:53] op_sel_hi:[1,0]
	s_nop 0
	v_pk_fma_f32 v[34:35], v[34:35], v[50:51], v[36:37] op_sel_hi:[1,0,1]
	v_pk_mul_f32 v[36:37], v[112:113], v[60:61] op_sel_hi:[1,0]
	s_nop 0
	v_pk_fma_f32 v[216:217], v[34:35], v[58:59], v[36:37] op_sel_hi:[1,0,1]
	s_cbranch_scc1 .LBB0_1285
	s_waitcnt vmcnt(17)
	v_mov_b64_e32 v[34:35], v[90:91]
	s_waitcnt vmcnt(12)
	v_mov_b64_e32 v[38:39], v[82:83]
	s_waitcnt vmcnt(7)
	v_mov_b64_e32 v[46:47], v[106:107]
	v_mov_b64_e32 v[42:43], v[150:151]
	v_mov_b64_e32 v[50:51], v[98:99]
	s_waitcnt vmcnt(6)
	v_mov_b64_e32 v[58:59], v[130:131]
	v_mov_b64_e32 v[36:37], v[92:93]
	v_mov_b64_e32 v[40:41], v[84:85]
	v_mov_b64_e32 v[48:49], v[108:109]
	v_mov_b64_e32 v[44:45], v[152:153]
	v_mov_b64_e32 v[52:53], v[100:101]
	v_mov_b64_e32 v[60:61], v[132:133]
	s_waitcnt vmcnt(5)
	v_mov_b32_e32 v226, v235
	v_mov_b32_e32 v227, v234
	v_mov_b32_e32 v228, v233
	s_branch .LBB0_1251
.LBB0_1285:
	s_waitcnt vmcnt(18)
	v_pk_mul_f32 v[16:17], v[208:209], v[16:17]
	v_pk_mul_f32 v[14:15], v[206:207], v[14:15]
	v_pk_mul_f32 v[12:13], v[204:205], v[12:13]
	v_pk_mov_b32 v[34:35], v[14:15], v[16:17] op_sel:[1,0]
	v_mov_b32_e32 v15, v17
	v_pk_mul_f32 v[10:11], v[202:203], v[10:11]
	v_pk_add_f32 v[14:15], v[34:35], v[14:15]
	v_mov_b32_e32 v16, v12
	v_mov_b32_e32 v17, v10
	v_mov_b32_e32 v10, v13
	v_pk_add_f32 v[10:11], v[16:17], v[10:11]
	v_add_f32_e32 v12, v14, v15
	v_add_f32_e32 v11, v12, v11
	v_add_f32_e32 v10, v10, v11
	s_waitcnt vmcnt(13)
	v_pk_mul_f32 v[24:25], v[208:209], v[24:25]
	v_pk_mul_f32 v[22:23], v[206:207], v[22:23]
	v_add_f32_dpp v10, v10, v10 quad_perm:[1,0,3,2] row_mask:0xf bank_mask:0xf bound_ctrl:1
	v_pk_mov_b32 v[34:35], v[22:23], v[24:25] op_sel:[1,0]
	v_mov_b32_e32 v23, v25
	v_add_f32_dpp v10, v10, v10 quad_perm:[2,3,0,1] row_mask:0xf bank_mask:0xf bound_ctrl:1
	v_pk_mul_f32 v[20:21], v[204:205], v[20:21]
	v_pk_mul_f32 v[18:19], v[202:203], v[18:19]
	v_add_f32_dpp v10, v10, v10 row_half_mirror row_mask:0xf bank_mask:0xf bound_ctrl:1
	v_pk_add_f32 v[22:23], v[34:35], v[22:23]
	v_mov_b32_e32 v24, v20
	v_mov_b32_e32 v25, v18
	v_mov_b32_e32 v18, v21
	v_add_f32_e32 v11, v233, v10
	v_max_f32_e32 v10, v225, v225
	v_pk_add_f32 v[18:19], v[24:25], v[18:19]
	v_add_f32_e32 v20, v22, v23
	v_max_f32_e32 v13, v10, v11
	v_add_f32_e32 v19, v20, v19
	v_sub_f32_e32 v11, v11, v13
	v_add_f32_e32 v18, v18, v19
	v_mul_f32_e32 v11, 0x3fb8aa3b, v11
	v_exp_f32_e32 v12, v11
	v_add_f32_dpp v18, v18, v18 quad_perm:[1,0,3,2] row_mask:0xf bank_mask:0xf bound_ctrl:1
	v_sub_f32_e32 v10, v225, v13
	s_waitcnt vmcnt(8)
	v_pk_mul_f32 v[24:25], v[206:207], v[30:31]
	v_add_f32_dpp v18, v18, v18 quad_perm:[2,3,0,1] row_mask:0xf bank_mask:0xf bound_ctrl:1
	v_pk_mul_f32 v[14:15], v[150:151], v[12:13] op_sel_hi:[1,0]
	v_pk_mul_f32 v[16:17], v[152:153], v[12:13] op_sel_hi:[1,0]
	v_add_f32_dpp v18, v18, v18 row_half_mirror row_mask:0xf bank_mask:0xf bound_ctrl:1
	v_add_f32_e32 v18, v234, v18
	v_max_f32_e32 v21, v13, v18
	v_sub_f32_e32 v13, v13, v21
	v_mul_f32_e32 v13, 0x3fb8aa3b, v13
	v_exp_f32_e32 v20, v13
	v_sub_f32_e32 v13, v18, v21
	v_pk_mul_f32 v[18:19], v[208:209], v[32:33]
	v_pk_mul_f32 v[26:27], v[202:203], v[26:27]
	v_pk_mov_b32 v[30:31], v[24:25], v[18:19] op_sel:[1,0]
	v_mov_b32_e32 v25, v19
	v_pk_add_f32 v[18:19], v[30:31], v[24:25]
	v_pk_mul_f32 v[24:25], v[204:205], v[28:29]
	v_mul_f32_e32 v13, 0x3fb8aa3b, v13
	v_mov_b32_e32 v28, v24
	v_mov_b32_e32 v29, v26
	v_mov_b32_e32 v26, v25
	v_exp_f32_e32 v22, v13
	v_pk_add_f32 v[24:25], v[28:29], v[26:27]
	v_add_f32_e32 v13, v18, v19
	v_add_f32_e32 v13, v13, v25
	v_add_f32_e32 v13, v24, v13
	s_waitcnt vmcnt(3)
; __device__ __forceinline__ unsigned pk2(float lo, float hi) { f32x2_p v = {lo, hi}; bf16x2_p b = __builtin_convertvector(v, bf16x2_p); return __builtin_bit_cast(unsigned, b); }
; __device__ __forceinline__ void p_attn_sample(const float* P, const float* ck, const float* cv, const float* relb, bf16* heads, const float* sbt, unsigned* qctr, volatile LAS unsigned* slot, int wave, int lane_in) {
;     ...
;         SLOADB(ak0, ak1, av0, av1, ab, 0)
; #pragma unroll 1
;         for (int it0 = 0; it0 < 48; it0 += 8) {
;             SLOADB(bk0, bk1, bv0, bv1, bbv, it0 + 4)
;             SPROCB(ak0, ak1, av0, av1, ab)
;             SLOADB(ak0, ak1, av0, av1, ab, it0 + 8)
;             SPROCB(bk0, bk1, bv0, bv1, bbv)
;         }
;         SPROCB(ak0, ak1, av0, av1, ab)
;     ...
;         float mt = fmaxf(mx, __shfl_xor(mx, 8)); mt = fmaxf(mt, __shfl_xor(mt, 16)); mt = fmaxf(mt, __shfl_xor(mt, 32));
;         const float fs = __expf(mx - mt); sum *= fs;
;         sum += __shfl_xor(sum, 8); sum += __shfl_xor(sum, 16); sum += __shfl_xor(sum, 32);
; #pragma unroll
;         for (int j = 0; j < 8; ++j) { acc[j] *= fs; acc[j] += __shfl_xor(acc[j], 8); acc[j] += __shfl_xor(acc[j], 16); acc[j] += __shfl_xor(acc[j], 32); }
;         if (g == 0) { const float inv = 1.0f / sum; v4u o; o.x = pk2(acc[0] * inv, acc[1] * inv); o.y = pk2(acc[2] * inv, acc[3] * inv); o.z = pk2(acc[4] * inv, acc[5] * inv); o.w = pk2(acc[6] * inv, acc[7] * inv);
	v_pk_mul_f32 v[18:19], v[208:209], v[76:77]
	v_pk_mul_f32 v[24:25], v[206:207], v[74:75]
	v_add_f32_dpp v13, v13, v13 quad_perm:[1,0,3,2] row_mask:0xf bank_mask:0xf bound_ctrl:1
	v_pk_mov_b32 v[26:27], v[24:25], v[18:19] op_sel:[1,0]
	v_mov_b32_e32 v25, v19
	v_pk_add_f32 v[18:19], v[26:27], v[24:25]
	v_pk_mul_f32 v[24:25], v[204:205], v[72:73]
	v_pk_mul_f32 v[26:27], v[202:203], v[70:71]
	v_mov_b32_e32 v28, v24
	v_mov_b32_e32 v29, v26
	v_mov_b32_e32 v26, v25
	v_pk_add_f32 v[24:25], v[28:29], v[26:27]
	v_add_f32_e32 v18, v18, v19
	v_add_f32_e32 v18, v18, v25
	v_add_f32_e32 v18, v24, v18
	v_add_f32_dpp v13, v13, v13 quad_perm:[2,3,0,1] row_mask:0xf bank_mask:0xf bound_ctrl:1
	v_and_b32_e32 v25, 64, v197
	v_add_f32_dpp v18, v18, v18 quad_perm:[1,0,3,2] row_mask:0xf bank_mask:0xf bound_ctrl:1
	v_add_f32_dpp v13, v13, v13 row_half_mirror row_mask:0xf bank_mask:0xf bound_ctrl:1
	v_xor_b32_e32 v24, 8, v197
	v_add_f32_dpp v18, v18, v18 quad_perm:[2,3,0,1] row_mask:0xf bank_mask:0xf bound_ctrl:1
	v_add_u32_e32 v25, 64, v25
	v_add_f32_e32 v13, v235, v13
	v_add_f32_dpp v18, v18, v18 row_half_mirror row_mask:0xf bank_mask:0xf bound_ctrl:1
	v_cmp_lt_i32_e32 vcc, v24, v25
	v_max_f32_e32 v23, v21, v13
	s_waitcnt vmcnt(0)
	v_add_f32_e32 v18, v222, v18
	v_cndmask_b32_e32 v24, v197, v24, vcc
	v_max_f32_e32 v19, v23, v18
	v_lshlrev_b32_e32 v27, 2, v24
	ds_bpermute_b32 v26, v27, v19
	v_sub_f32_e32 v21, v21, v23
	v_mul_f32_e32 v21, 0x3fb8aa3b, v21
	v_exp_f32_e32 v24, v21
	v_sub_f32_e32 v13, v13, v23
	s_waitcnt lgkmcnt(0)
	v_max_f32_e32 v21, v26, v26
	v_xor_b32_e32 v26, 16, v197
	v_cmp_lt_i32_e32 vcc, v26, v25
	v_max_f32_e32 v21, v19, v21
	v_mul_f32_e32 v13, 0x3fb8aa3b, v13
	v_cndmask_b32_e32 v26, v197, v26, vcc
	v_lshlrev_b32_e32 v29, 2, v26
	ds_bpermute_b32 v28, v29, v21
	v_exp_f32_e32 v26, v13
	v_sub_f32_e32 v13, v23, v19
	v_mul_f32_e32 v13, 0x3fb8aa3b, v13
	v_mul_f32_e32 v10, 0x3fb8aa3b, v10
	s_waitcnt lgkmcnt(0)
	v_max_f32_e32 v23, v28, v28
	v_max_f32_e32 v21, v21, v23
	v_xor_b32_e32 v23, 32, v197
	v_cmp_lt_i32_e32 vcc, v23, v25
	v_exp_f32_e32 v28, v13
	v_sub_f32_e32 v13, v18, v19
	v_cndmask_b32_e32 v23, v197, v23, vcc
	v_lshlrev_b32_e32 v25, 2, v23
	ds_bpermute_b32 v23, v25, v21
	v_mul_f32_e32 v13, 0x3fb8aa3b, v13
	v_exp_f32_e32 v10, v10
	v_exp_f32_e32 v30, v13
	s_waitcnt lgkmcnt(0)
	v_max_f32_e32 v13, v23, v23
	v_max_f32_e32 v13, v21, v13
	v_sub_f32_e32 v13, v19, v13
	v_mul_f32_e32 v13, 0x3fb8aa3b, v13
	v_fma_f32 v11, v224, v10, v12
	v_exp_f32_e32 v32, v13
	v_pk_fma_f32 v[14:15], v[220:221], v[10:11], v[14:15] op_sel_hi:[1,0,1]
	v_pk_fma_f32 v[16:17], v[218:219], v[10:11], v[16:17] op_sel_hi:[1,0,1]
	v_fma_f32 v11, v11, v20, v22
	v_fma_f32 v11, v11, v24, v26
	v_fma_f32 v11, v11, v28, v30
	v_mul_f32_e32 v13, v11, v32
	ds_bpermute_b32 v21, v27, v13
	v_pk_mul_f32 v[18:19], v[90:91], v[12:13] op_sel_hi:[1,0]
	v_pk_mul_f32 v[12:13], v[92:93], v[12:13] op_sel_hi:[1,0]
	v_pk_fma_f32 v[34:35], v[214:215], v[10:11], v[18:19] op_sel_hi:[1,0,1]
	v_pk_fma_f32 v[12:13], v[216:217], v[10:11], v[12:13] op_sel_hi:[1,0,1]
	s_waitcnt lgkmcnt(0)
	v_fmac_f32_e32 v21, v11, v32
	v_pk_mul_f32 v[10:11], v[98:99], v[22:23] op_sel_hi:[1,0]
	v_pk_mul_f32 v[8:9], v[8:9], v[30:31] op_sel_hi:[1,0]
	v_pk_fma_f32 v[10:11], v[14:15], v[20:21], v[10:11] op_sel_hi:[1,0,1]
	v_pk_mul_f32 v[14:15], v[130:131], v[26:27] op_sel_hi:[1,0]
	v_pk_mul_f32 v[2:3], v[2:3], v[30:31] op_sel_hi:[1,0]
	v_pk_fma_f32 v[10:11], v[10:11], v[24:25], v[14:15] op_sel_hi:[1,0,1]
	v_pk_mul_f32 v[14:15], v[100:101], v[22:23] op_sel_hi:[1,0]
	v_pk_mul_f32 v[6:7], v[6:7], v[30:31] op_sel_hi:[1,0]
	v_pk_fma_f32 v[14:15], v[16:17], v[20:21], v[14:15] op_sel_hi:[1,0,1]
	v_pk_mul_f32 v[16:17], v[132:133], v[26:27] op_sel_hi:[1,0]
	v_pk_mul_f32 v[4:5], v[4:5], v[30:31] op_sel_hi:[1,0]
	v_pk_fma_f32 v[14:15], v[14:15], v[24:25], v[16:17] op_sel_hi:[1,0,1]
	v_pk_mul_f32 v[16:17], v[106:107], v[26:27] op_sel_hi:[1,0]
	v_pk_fma_f32 v[8:9], v[14:15], v[28:29], v[8:9] op_sel_hi:[1,0,1]
	v_pk_fma_f32 v[6:7], v[10:11], v[28:29], v[6:7] op_sel_hi:[1,0,1]
	v_pk_mul_f32 v[14:15], v[8:9], v[32:33] op_sel_hi:[1,0]
	ds_bpermute_b32 v14, v27, v14
	ds_bpermute_b32 v15, v27, v15
	v_pk_mul_f32 v[10:11], v[6:7], v[32:33] op_sel_hi:[1,0]
	ds_bpermute_b32 v18, v29, v21
	ds_bpermute_b32 v10, v27, v10
	ds_bpermute_b32 v11, v27, v11
	s_waitcnt lgkmcnt(3)
	v_pk_fma_f32 v[8:9], v[8:9], v[32:33], v[14:15] op_sel_hi:[1,0,1]
	ds_bpermute_b32 v14, v29, v8
	ds_bpermute_b32 v15, v29, v9
	s_waitcnt lgkmcnt(4)
	v_add_f32_e32 v18, v21, v18
	s_waitcnt lgkmcnt(2)
	v_pk_fma_f32 v[6:7], v[6:7], v[32:33], v[10:11] op_sel_hi:[1,0,1]
	ds_bpermute_b32 v10, v29, v6
	ds_bpermute_b32 v11, v29, v7
	s_waitcnt lgkmcnt(2)
	v_pk_add_f32 v[8:9], v[8:9], v[14:15]
	v_pk_mul_f32 v[14:15], v[82:83], v[22:23] op_sel_hi:[1,0]
	ds_bpermute_b32 v19, v25, v18
	v_pk_fma_f32 v[14:15], v[34:35], v[20:21], v[14:15] op_sel_hi:[1,0,1]
	s_waitcnt lgkmcnt(1)
	v_pk_add_f32 v[6:7], v[6:7], v[10:11]
	v_pk_fma_f32 v[14:15], v[14:15], v[24:25], v[16:17] op_sel_hi:[1,0,1]
	ds_bpermute_b32 v10, v25, v6
	v_pk_fma_f32 v[14:15], v[14:15], v[28:29], v[2:3] op_sel_hi:[1,0,1]
	ds_bpermute_b32 v11, v25, v7
	v_pk_mul_f32 v[2:3], v[14:15], v[32:33] op_sel_hi:[1,0]
	ds_bpermute_b32 v16, v27, v2
	ds_bpermute_b32 v17, v27, v3
	v_pk_mul_f32 v[2:3], v[84:85], v[22:23] op_sel_hi:[1,0]
	s_waitcnt lgkmcnt(0)
	v_pk_fma_f32 v[14:15], v[14:15], v[32:33], v[16:17] op_sel_hi:[1,0,1]
	v_pk_fma_f32 v[2:3], v[12:13], v[20:21], v[2:3] op_sel_hi:[1,0,1]
	v_pk_mul_f32 v[12:13], v[108:109], v[26:27] op_sel_hi:[1,0]
	ds_bpermute_b32 v16, v29, v14
	v_pk_fma_f32 v[2:3], v[2:3], v[24:25], v[12:13] op_sel_hi:[1,0,1]
	ds_bpermute_b32 v17, v29, v15
	v_pk_fma_f32 v[4:5], v[2:3], v[28:29], v[4:5] op_sel_hi:[1,0,1]
	s_nop 0
	v_pk_mul_f32 v[2:3], v[4:5], v[32:33] op_sel_hi:[1,0]
	ds_bpermute_b32 v12, v27, v2
	ds_bpermute_b32 v13, v27, v3
	ds_bpermute_b32 v2, v25, v8
	ds_bpermute_b32 v3, v25, v9
	s_waitcnt lgkmcnt(2)
	v_pk_fma_f32 v[20:21], v[4:5], v[32:33], v[12:13] op_sel_hi:[1,0,1]
	ds_bpermute_b32 v22, v29, v20
	ds_bpermute_b32 v23, v29, v21
	v_pk_add_f32 v[4:5], v[14:15], v[16:17]
	ds_bpermute_b32 v12, v25, v4
	ds_bpermute_b32 v13, v25, v5
	s_waitcnt lgkmcnt(2)
	v_pk_add_f32 v[14:15], v[20:21], v[22:23]
	ds_bpermute_b32 v16, v25, v14
	ds_bpermute_b32 v17, v25, v15
	s_and_saveexec_b64 s[0:1], s[4:5]
	s_xor_b64 s[0:1], exec, s[0:1]
	s_cbranch_execz .LBB0_1243
; __device__ __forceinline__ unsigned pk2(float lo, float hi) { f32x2_p v = {lo, hi}; bf16x2_p b = __builtin_convertvector(v, bf16x2_p); return __builtin_bit_cast(unsigned, b); }
; __device__ __forceinline__ void p_attn_sample(const float* P, const float* ck, const float* cv, const float* relb, bf16* heads, const float* sbt, unsigned* qctr, volatile LAS unsigned* slot, int wave, int lane_in) {
;     ...
;         if (g == 0) { const float inv = 1.0f / sum; v4u o; o.x = pk2(acc[0] * inv, acc[1] * inv); o.y = pk2(acc[2] * inv, acc[3] * inv); o.z = pk2(acc[4] * inv, acc[5] * inv); o.w = pk2(acc[6] * inv, acc[7] * inv);
;             *(v4u*)(heads + (size_t)m * DM + h * 64 + 8 * c) = o; }
	v_add_f32_e32 v18, v18, v19
	v_div_scale_f32 v19, s[14:15], v18, v18, 1.0
	v_rcp_f32_e32 v20, v19
	v_div_scale_f32 v21, vcc, 1.0, v18, 1.0
	v_pk_add_f32 v[6:7], v[6:7], v[10:11]
	v_fma_f32 v22, -v19, v20, 1.0
	v_fmac_f32_e32 v20, v22, v20
	v_mul_f32_e32 v22, v21, v20
	v_fma_f32 v23, -v19, v22, v21
	v_fmac_f32_e32 v22, v23, v20
	v_fma_f32 v19, -v19, v22, v21
	v_div_fmas_f32 v19, v19, v20, v22
	v_div_fixup_f32 v18, v19, v18, 1.0
	v_pk_add_f32 v[2:3], v[8:9], v[2:3]
	v_pk_mul_f32 v[6:7], v[6:7], v[18:19] op_sel_hi:[1,0]
	v_pk_mul_f32 v[2:3], v[18:19], v[2:3] op_sel_hi:[0,1]
	v_cvt_pk_bf16_f32 v6, v6, v7
	v_cvt_pk_bf16_f32 v7, v2, v3
	s_waitcnt lgkmcnt(2)
	v_pk_add_f32 v[2:3], v[4:5], v[12:13]
	s_lshl_b32 s2, s2, 11
	v_pk_mul_f32 v[2:3], v[18:19], v[2:3] op_sel_hi:[0,1]
	s_add_u32 s2, s48, s2
	v_cvt_pk_bf16_f32 v8, v2, v3
	s_waitcnt lgkmcnt(0)
	v_pk_add_f32 v[2:3], v[14:15], v[16:17]
	s_addc_u32 s3, s49, 0
	s_lshl_b32 s14, s22, 1
	v_pk_mul_f32 v[2:3], v[18:19], v[2:3] op_sel_hi:[0,1]
	s_add_u32 s2, s2, s14
	v_cvt_pk_bf16_f32 v9, v2, v3
	s_addc_u32 s3, s3, 0
	global_store_dwordx2 v154, v[6:7], s[2:3]
	global_store_dwordx2 v154, v[8:9], s[2:3] offset:64
	s_branch .LBB0_1243

; __device__ __forceinline__ void p_attn_sample(const float* P, const float* ck, const float* cv, const float* relb, bf16* heads, const float* sbt, unsigned* qctr, volatile LAS unsigned* slot, int wave, int lane_in) {
;     ...
;     const int g = lane >> 3, c = lane & 7;
;     for (;;) {
;         __syncthreads(); if (threadIdx.x == 0) *slot = __hip_atomic_fetch_add(qctr, 1u, __ATOMIC_RELAXED, __HIP_MEMORY_SCOPE_AGENT); __syncthreads();
;         const unsigned wt = *slot; if (wt >= (unsigned)(DB * 4)) break;
;         const int b = (int)(wt >> 2), t = wave & 3, h = 2 * (int)(wt & 3u) + (wave >> 2), sr = 4 * b + t, m = MP + sr, p = SEQ + t;
;         f32x4 q0 = *(const f32x4*)(P + (size_t)m * NINP + C_AQ + h * 64 + 8 * c), q1 = *(const f32x4*)(P + (size_t)m * NINP + C_AQ + h * 64 + 8 * c + 4);
;         q0 = q0 * 0.125f; q1 = q1 * 0.125f;
;         const float* knew = P + (size_t)(MP + b * DS) * NINP + C_AK + h * 64 + 8 * c; const float* kold = ck + ((size_t)b * SEQ * NH + h) * HD + 8 * c;
;         const float* vold = cv + ((size_t)b * SEQ * NH + h) * HD + 8 * c;
;         const float* sbh = sbt + h * 392;
;         float mx = -INFINITY, sum = 0.f; float acc[8];
; #pragma unroll
;         for (int j = 0; j < 8; ++j) acc[j] = 0.f;
;         f32x4 ak0[4], ak1[4], av0[4], av1[4], bk0[4], bk1[4], bv0[4], bv1[4]; float ab[4], bbv[4];
.LBB0_1373:
	s_andn2_b64 vcc, exec, s[20:21]
	s_cbranch_vccnz .LBB0_1419
	s_movk_i32 s19, 0x80
	v_ashrrev_i32_e32 v18, 3, v196
	v_cmp_lt_i32_e32 vcc, s19, v18
	s_movk_i32 s23, 0x102
	v_readlane_b32 s0, v245, 0
	v_cndmask_b32_e64 v3, 0, 1, vcc
	v_cmp_gt_i32_e32 vcc, s23, v18
	v_lshlrev_b32_e32 v2, 3, v196
	s_bfe_u32 s33, s0, 0x20006
	v_cndmask_b32_e32 v3, 2, v3, vcc
	v_and_b32_e32 v154, 56, v2
	v_min_i32_e32 v2, 0x182, v18
	v_mul_i32_i24_e32 v4, 0xffffff7f, v3
	v_lshlrev_b32_e32 v3, 1, v3
	s_or_b32 s18, s33, 0x800
	v_add_lshl_u32 v2, v4, v2, v3
	v_sub_u32_e32 v2, s18, v2
	s_lshr_b32 s16, s0, 8
	v_readlane_b32 s0, v245, 5
	v_ashrrev_i32_e32 v3, 31, v2
	v_readlane_b32 s1, v245, 6
	v_lshlrev_b64 v[162:163], 11, v[2:3]
	v_add_u32_e32 v3, 0xfffff800, v2
	s_movk_i32 s27, 0x3c00
	v_mad_u64_u32 v[164:165], s[0:1], v3, s27, 0
	s_movk_i32 s0, 0x78
	v_mov_b32_e32 v157, 0
	v_cmp_lt_i32_e32 vcc, s0, v18
	s_movk_i32 s0, 0xfa
	v_mov_b32_e32 v3, v157
	v_cndmask_b32_e64 v7, 0, 1, vcc
	v_cmp_gt_i32_e32 vcc, s0, v18
	v_lshlrev_b64 v[4:5], 11, v[2:3]
	v_add_u32_e32 v3, 8, v18
	v_cndmask_b32_e32 v7, 2, v7, vcc
	v_min_i32_e32 v6, 0x182, v3
	v_mul_i32_i24_e32 v8, 0xffffff7f, v7
	v_lshlrev_b32_e32 v7, 1, v7
	v_add_lshl_u32 v6, v8, v6, v7
	v_sub_u32_e32 v6, s18, v6
	v_ashrrev_i32_e32 v7, 31, v6
	v_lshlrev_b64 v[168:169], 11, v[6:7]
	v_add_u32_e32 v7, 0xfffff800, v6
	v_mad_u64_u32 v[170:171], s[0:1], v7, s27, 0
	s_movk_i32 s0, 0x70
	s_nop 0
	v_cmp_lt_i32_e32 vcc, s0, v18
	s_movk_i32 s0, 0xf2
	v_mov_b32_e32 v7, v157
	v_cndmask_b32_e64 v10, 0, 1, vcc
	v_cmp_gt_i32_e32 vcc, s0, v18
	v_min_i32_e32 v172, 0x187, v3
	v_add_u32_e32 v3, 16, v18
	v_cndmask_b32_e32 v10, 2, v10, vcc
	v_lshlrev_b64 v[8:9], 11, v[6:7]
	v_min_i32_e32 v7, 0x182, v3
	v_mul_i32_i24_e32 v11, 0xffffff7f, v10
	v_lshlrev_b32_e32 v10, 1, v10
	v_add_lshl_u32 v7, v11, v7, v10
	v_sub_u32_e32 v10, s18, v7
	v_add_u32_e32 v7, 0xfffff800, v10
	v_mad_u64_u32 v[176:177], s[0:1], v7, s27, 0
	v_ashrrev_i32_e32 v11, 31, v10
	s_movk_i32 s0, 0x68
	v_lshlrev_b64 v[174:175], 11, v[10:11]
	v_mov_b32_e32 v11, v157
	v_cmp_lt_i32_e32 vcc, s0, v18
	s_movk_i32 s0, 0xea
	v_lshlrev_b64 v[12:13], 11, v[10:11]
	v_cndmask_b32_e64 v11, 0, 1, vcc
	v_cmp_gt_i32_e32 vcc, s0, v18
	v_min_i32_e32 v178, 0x187, v3
	v_add_u32_e32 v3, 24, v18
	v_cndmask_b32_e32 v11, 2, v11, vcc
	v_min_i32_e32 v7, 0x182, v3
	v_mul_i32_i24_e32 v14, 0xffffff7f, v11
	v_lshlrev_b32_e32 v11, 1, v11
	v_add_lshl_u32 v7, v14, v7, v11
	v_sub_u32_e32 v14, s18, v7
	v_ashrrev_i32_e32 v15, 31, v14
	v_lshlrev_b32_e32 v156, 1, v154
	v_readlane_b32 s6, v245, 11
	v_readlane_b32 s7, v245, 12
	v_readlane_b32 s8, v245, 13
	v_readlane_b32 s9, v245, 14
	v_readlane_b32 s10, v245, 15
	v_readlane_b32 s11, v245, 16
	v_readlane_b32 s12, v245, 17
	v_readlane_b32 s13, v245, 18
	s_movk_i32 s26, 0x7ff
	v_lshlrev_b64 v[180:181], 11, v[14:15]
	v_mov_b32_e32 v15, v157
	v_readlane_b32 s4, v245, 9
	v_readlane_b32 s5, v245, 10
	v_lshl_add_u64 v[160:161], s[6:7], 0, v[156:157]
	v_min_i32_e32 v166, 0x187, v18
	v_add_u32_e32 v7, 0xfffff800, v14
	v_lshlrev_b64 v[16:17], 11, v[14:15]
	v_min_i32_e32 v184, 0x187, v3
	v_cmp_lt_i32_e64 s[6:7], s26, v2
	v_cmp_lt_i32_e64 s[8:9], s26, v6
	v_cmp_lt_i32_e64 s[10:11], s26, v10
	v_cmp_lt_i32_e64 s[12:13], s26, v14
	s_movk_i32 s17, 0x800
	v_lshl_add_u64 v[158:159], s[4:5], 0, v[156:157]
	v_cmp_gt_u32_e64 s[4:5], 8, v196
	v_ashrrev_i32_e32 v167, 31, v166
	v_ashrrev_i32_e32 v173, 31, v172
	v_ashrrev_i32_e32 v179, 31, v178
	v_mad_u64_u32 v[182:183], s[0:1], v7, s27, 0
	v_ashrrev_i32_e32 v185, 31, v184
	v_add_u32_e32 v155, 0x58, v18
	v_cndmask_b32_e64 v187, v163, v5, s[6:7]
	v_cndmask_b32_e64 v186, v162, v4, s[6:7]
	v_cndmask_b32_e64 v189, v169, v9, s[8:9]
	v_cndmask_b32_e64 v188, v168, v8, s[8:9]
	v_cndmask_b32_e64 v191, v175, v13, s[10:11]
	v_cndmask_b32_e64 v190, v174, v12, s[10:11]
	v_cndmask_b32_e64 v193, v181, v17, s[12:13]
	v_cndmask_b32_e64 v192, v180, v16, s[12:13]
	s_bitset1_b32 s33, 14
	s_mov_b32 s21, 0
	s_add_i32 s34, 0, 0x23f84
	s_movk_i32 s35, 0x1ff
	s_mov_b32 s22, 0x3e000000
	s_mov_b64 s[24:25], 0xf000800
	s_mov_b64 s[28:29], 0x800
	v_mbcnt_hi_u32_b32 v220, -1, v1
	v_readlane_b32 s2, v245, 7
	v_readlane_b32 s3, v245, 8
	v_readlane_b32 s14, v245, 19
	v_readlane_b32 s15, v245, 20
	s_branch .LBB0_1377

; __device__ __forceinline__ void p_attn_sample(const float* P, const float* ck, const float* cv, const float* relb, bf16* heads, const float* sbt, unsigned* qctr, volatile LAS unsigned* slot, int wave, int lane_in) {
;     ...
;         __syncthreads(); if (threadIdx.x == 0) *slot = __hip_atomic_fetch_add(qctr, 1u, __ATOMIC_RELAXED, __HIP_MEMORY_SCOPE_AGENT); __syncthreads();
;         const unsigned wt = *slot; if (wt >= (unsigned)(DB * 4)) break;
;         const int b = (int)(wt >> 2), t = wave & 3, h = 2 * (int)(wt & 3u) + (wave >> 2), sr = 4 * b + t, m = MP + sr, p = SEQ + t;
;         f32x4 q0 = *(const f32x4*)(P + (size_t)m * NINP + C_AQ + h * 64 + 8 * c), q1 = *(const f32x4*)(P + (size_t)m * NINP + C_AQ + h * 64 + 8 * c + 4);
;         q0 = q0 * 0.125f; q1 = q1 * 0.125f;
;         const float* knew = P + (size_t)(MP + b * DS) * NINP + C_AK + h * 64 + 8 * c; const float* kold = ck + ((size_t)b * SEQ * NH + h) * HD + 8 * c;
;         const float* vold = cv + ((size_t)b * SEQ * NH + h) * HD + 8 * c;
;         const float* sbh = sbt + h * 392;
;         float mx = -INFINITY, sum = 0.f; float acc[8];
; #pragma unroll
;         for (int j = 0; j < 8; ++j) acc[j] = 0.f;
;         f32x4 ak0[4], ak1[4], av0[4], av1[4], bk0[4], bk1[4], bv0[4], bv1[4]; float ab[4], bbv[4];
;     ...
;         SLOADB(ak0, ak1, av0, av1, ab, 0)
.LBB0_1381:
	s_or_b64 exec, exec, s[0:1]
	v_mov_b32_e32 v2, s34
	s_waitcnt lgkmcnt(0)
	s_barrier
	ds_read_b32 v2, v2
	s_mov_b64 s[0:1], -1
	s_waitcnt lgkmcnt(0)
	v_cmp_lt_u32_e32 vcc, s35, v2
	v_readfirstlane_b32 s3, v2
	s_cbranch_vccnz .LBB0_1376
	s_lshl_b32 s0, s3, 1
	s_and_b32 s31, s3, 0x1fc
	s_and_b32 s0, s0, 6
	s_or_b32 s2, s31, s33
	s_add_i32 s30, s0, s16
	s_mul_i32 s0, s2, 0x3c00
	s_add_u32 s14, s88, s0
	s_addc_u32 s15, s89, 0
	s_lshl_b32 s20, s30, 6
	s_lshl_b64 s[0:1], s[20:21], 2
	s_add_u32 s14, s14, s0
	s_addc_u32 s15, s15, s1
	v_lshlrev_b32_e32 v156, 1, v154
	s_mulk_i32 s31, 0x3c00
	global_load_dwordx4 v[54:57], v156, s[14:15] offset:128
	global_load_dwordx4 v[62:65], v156, s[14:15]
	s_add_u32 s14, s88, s31
	s_addc_u32 s15, s89, 0
	s_add_u32 s0, s14, s0
	s_addc_u32 s1, s15, s1
	s_lshl_b32 s3, s3, 12
	s_and_b32 s3, s3, 0x1fc000
	s_add_i32 s3, s30, s3
	s_lshl_b32 s14, s3, 6
	s_mov_b32 s15, s21
	s_lshl_b64 s[14:15], s[14:15], 2
	v_lshl_add_u64 v[2:3], s[0:1], 0, v[156:157]
	v_lshl_add_u64 v[194:195], v[158:159], 0, s[14:15]
	v_lshl_add_u64 v[196:197], v[2:3], 0, s[24:25]
	v_lshl_add_u64 v[2:3], v[194:195], 0, v[162:163]
	v_lshl_add_u64 v[4:5], v[196:197], 0, v[164:165]
	v_lshl_add_u64 v[198:199], v[160:161], 0, s[14:15]
	v_cndmask_b32_e64 v3, v3, v5, s[6:7]
	v_cndmask_b32_e64 v2, v2, v4, s[6:7]
	v_lshl_add_u64 v[4:5], v[2:3], 0, s[28:29]
	v_lshl_add_u64 v[6:7], v[198:199], 0, v[186:187]
	v_cndmask_b32_e64 v5, v7, v5, s[6:7]
	v_cndmask_b32_e64 v4, v6, v4, s[6:7]
	global_load_dwordx4 v[14:17], v[2:3], off
	global_load_dwordx4 v[10:13], v[2:3], off offset:128
	global_load_dwordx4 v[34:37], v[4:5], off offset:128
	global_load_dwordx4 v[42:45], v[4:5], off
	v_lshl_add_u64 v[2:3], v[196:197], 0, v[170:171]
	v_lshl_add_u64 v[4:5], v[194:195], 0, v[168:169]
	v_cndmask_b32_e64 v3, v5, v3, s[8:9]
	v_cndmask_b32_e64 v2, v4, v2, s[8:9]
	v_lshl_add_u64 v[4:5], v[2:3], 0, s[28:29]
	v_lshl_add_u64 v[6:7], v[198:199], 0, v[188:189]
	v_cndmask_b32_e64 v5, v7, v5, s[8:9]
	v_cndmask_b32_e64 v4, v6, v4, s[8:9]
	global_load_dwordx4 v[22:25], v[2:3], off
	global_load_dwordx4 v[18:21], v[2:3], off offset:128
	global_load_dwordx4 v[38:41], v[4:5], off offset:128
	global_load_dwordx4 v[50:53], v[4:5], off
	v_lshl_add_u64 v[2:3], v[196:197], 0, v[176:177]
	v_lshl_add_u64 v[4:5], v[194:195], 0, v[174:175]
	v_cndmask_b32_e64 v3, v5, v3, s[10:11]
	v_cndmask_b32_e64 v2, v4, v2, s[10:11]
	v_lshl_add_u64 v[4:5], v[2:3], 0, s[28:29]
	v_lshl_add_u64 v[6:7], v[198:199], 0, v[190:191]
	s_mulk_i32 s30, 0x188
	s_mov_b32 s31, s21
	v_cndmask_b32_e64 v5, v7, v5, s[10:11]
	v_cndmask_b32_e64 v4, v6, v4, s[10:11]
	s_lshl_b64 s[0:1], s[30:31], 2
	v_readlane_b32 s14, v245, 37
	global_load_dwordx4 v[30:33], v[2:3], off
	global_load_dwordx4 v[26:29], v[2:3], off offset:128
	global_load_dwordx4 v[46:49], v[4:5], off offset:128
	global_load_dwordx4 v[58:61], v[4:5], off
	v_lshl_add_u64 v[2:3], v[196:197], 0, v[182:183]
	v_lshl_add_u64 v[4:5], v[194:195], 0, v[180:181]
	v_readlane_b32 s15, v245, 38
	s_add_u32 s30, s14, s0
	v_cndmask_b32_e64 v3, v5, v3, s[12:13]
	v_cndmask_b32_e64 v2, v4, v2, s[12:13]
	s_addc_u32 s31, s15, s1
	v_lshl_add_u64 v[4:5], v[2:3], 0, s[28:29]
	v_lshl_add_u64 v[6:7], v[198:199], 0, v[192:193]
	v_lshl_add_u64 v[66:67], v[166:167], 2, s[30:31]
	v_cndmask_b32_e64 v7, v7, v5, s[12:13]
	v_cndmask_b32_e64 v6, v6, v4, s[12:13]
	v_lshl_add_u64 v[68:69], v[172:173], 2, s[30:31]
	v_lshl_add_u64 v[78:79], v[178:179], 2, s[30:31]
	global_load_dwordx4 v[74:77], v[2:3], off
	global_load_dwordx4 v[70:73], v[2:3], off offset:128
	s_nop 0
	global_load_dwordx4 v[2:5], v[6:7], off offset:128
	s_nop 0
	global_load_dwordx4 v[6:9], v[6:7], off
	v_lshl_add_u64 v[80:81], v[184:185], 2, s[30:31]
	global_load_dword v227, v[66:67], off
	global_load_dword v226, v[68:69], off
	global_load_dword v225, v[78:79], off
	global_load_dword v221, v[80:81], off
	v_mov_b32_e32 v223, 0
	v_mov_b32_e32 v224, 0xff800000
	s_mov_b32 s3, -8
	v_mov_b32_e32 v222, v155
	v_mov_b32_e32 v218, 0
	v_mov_b32_e32 v219, v223
	v_mov_b32_e32 v216, 0
	v_mov_b32_e32 v217, v223
	v_mov_b32_e32 v212, 0
	v_mov_b32_e32 v213, v223
	v_mov_b32_e32 v214, 0
	v_mov_b32_e32 v215, v223
	s_waitcnt vmcnt(0)
	v_pk_mul_f32 v[202:203], v[56:57], s[22:23] op_sel_hi:[1,0]
	v_pk_mul_f32 v[206:207], v[64:65], s[22:23] op_sel_hi:[1,0]
	v_pk_mul_f32 v[204:205], v[62:63], s[22:23] op_sel_hi:[1,0]
	v_pk_mul_f32 v[200:201], v[54:55], s[22:23] op_sel_hi:[1,0]
	v_pk_mov_b32 v[208:209], v[204:205], v[206:207] op_sel:[1,0]
	v_mov_b32_e32 v210, v204
	v_mov_b32_e32 v211, v207
; __device__ __forceinline__ void p_attn_sample(const float* P, const float* ck, const float* cv, const float* relb, bf16* heads, const float* sbt, unsigned* qctr, volatile LAS unsigned* slot, int wave, int lane_in) {
;     ...
;         SLOADB(ak0, ak1, av0, av1, ab, 0)
; #pragma unroll 1
;         for (int it0 = 0; it0 < 48; it0 += 8) {
;             SLOADB(bk0, bk1, bv0, bv1, bbv, it0 + 4)
.LBB0_1383:
	v_subrev_u32_e32 v255, 56, v222
	v_min_i32_e32 v255, 0x187, v255
	v_lshl_add_u32 v255, v255, 2, s101
	ds_read_b32 v246, v255
	v_subrev_u32_e32 v255, 48, v222
	v_min_i32_e32 v255, 0x187, v255
	v_lshl_add_u32 v255, v255, 2, s101
	ds_read_b32 v247, v255
	v_subrev_u32_e32 v255, 40, v222
	v_min_i32_e32 v255, 0x187, v255
	v_lshl_add_u32 v255, v255, 2, s101
	ds_read_b32 v248, v255
	v_subrev_u32_e32 v255, 32, v222
	v_min_i32_e32 v255, 0x187, v255
	v_lshl_add_u32 v255, v255, 2, s101
	ds_read_b32 v249, v255
	v_subrev_u32_e32 v255, 24, v222
	v_min_i32_e32 v255, 0x187, v255
	v_lshl_add_u32 v255, v255, 2, s101
	ds_read_b32 v250, v255
	v_subrev_u32_e32 v255, 16, v222
	v_min_i32_e32 v255, 0x187, v255
	v_lshl_add_u32 v255, v255, 2, s101
	ds_read_b32 v251, v255
	v_subrev_u32_e32 v255, 8, v222
	v_min_i32_e32 v255, 0x187, v255
	v_lshl_add_u32 v255, v255, 2, s101
	ds_read_b32 v252, v255
	v_min_i32_e32 v255, 0x187, v222
	v_lshl_add_u32 v255, v255, 2, s101
	ds_read_b32 v253, v255
	s_waitcnt lgkmcnt(0)
	v_subrev_u32_e32 v66, 56, v222
	v_mov_b32_e32 v66, v246
	v_cmp_lt_i32_e32 vcc, s19, v66
	v_min_i32_e32 v54, 0x182, v66
	s_nop 0
	v_cndmask_b32_e64 v55, 0, 1, vcc
	v_cmp_gt_i32_e32 vcc, s23, v66
	s_nop 1
	v_cndmask_b32_e32 v55, 2, v55, vcc
	v_mul_i32_i24_e32 v56, 0xffffff7f, v55
	v_lshlrev_b32_e32 v55, 1, v55
	v_add_lshl_u32 v54, v56, v54, v55
	v_sub_u32_e32 v156, s18, v54
	v_cmp_lt_i32_e32 vcc, s26, v156
	v_cmp_gt_i32_e64 s[0:1], s17, v156
	s_and_saveexec_b64 s[14:15], s[0:1]
	s_xor_b64 s[0:1], exec, s[14:15]
	v_ashrrev_i32_e32 v55, 31, v156
	v_mov_b32_e32 v54, v156
	v_lshlrev_b64 v[56:57], 11, v[54:55]
	v_lshl_add_u64 v[54:55], v[194:195], 0, v[56:57]
	s_andn2_saveexec_b64 s[0:1], s[0:1]
	v_add_u32_e32 v54, 0xfffff800, v156
	v_mad_u64_u32 v[54:55], s[14:15], v54, s27, v[196:197]
	v_lshlrev_b64 v[56:57], 11, v[156:157]
	s_or_b64 exec, exec, s[0:1]
	v_lshl_add_u64 v[62:63], v[54:55], 0, s[28:29]
	v_lshl_add_u64 v[56:57], v[198:199], 0, v[56:57]
	v_cndmask_b32_e32 v63, v57, v63, vcc
	v_cndmask_b32_e32 v62, v56, v62, vcc
	v_min_i32_e32 v66, 0x187, v66
	global_load_dwordx4 v[102:105], v[54:55], off offset:128
	global_load_dwordx4 v[114:117], v[54:55], off
	s_nop 0
	global_load_dwordx4 v[54:57], v[62:63], off offset:128
	s_nop 0
	global_load_dwordx4 v[62:65], v[62:63], off
	v_ashrrev_i32_e32 v67, 31, v66
	v_lshl_add_u64 v[66:67], v[66:67], 2, s[30:31]
	global_load_dword v228, v[66:67], off
	v_subrev_u32_e32 v82, 48, v222
	v_mov_b32_e32 v82, v247
	v_cmp_lt_i32_e32 vcc, s19, v82
	v_min_i32_e32 v66, 0x182, v82
	s_nop 0
	v_cndmask_b32_e64 v67, 0, 1, vcc
	v_cmp_gt_i32_e32 vcc, s23, v82
	s_nop 1
	v_cndmask_b32_e32 v67, 2, v67, vcc
	v_mul_i32_i24_e32 v68, 0xffffff7f, v67
	v_lshlrev_b32_e32 v67, 1, v67
	v_add_lshl_u32 v66, v68, v66, v67
	v_sub_u32_e32 v68, s18, v66
	v_cmp_lt_i32_e32 vcc, s26, v68
	v_cmp_gt_i32_e64 s[0:1], s17, v68
	s_and_saveexec_b64 s[14:15], s[0:1]
	s_xor_b64 s[0:1], exec, s[14:15]
	v_ashrrev_i32_e32 v69, 31, v68
	v_lshlrev_b64 v[78:79], 11, v[68:69]
	v_lshl_add_u64 v[66:67], v[194:195], 0, v[78:79]
	s_andn2_saveexec_b64 s[0:1], s[0:1]
	v_add_u32_e32 v66, 0xfffff800, v68
	v_mov_b32_e32 v69, v157
	v_mad_u64_u32 v[66:67], s[14:15], v66, s27, v[196:197]
	v_lshlrev_b64 v[78:79], 11, v[68:69]
	s_or_b64 exec, exec, s[0:1]
	v_lshl_add_u64 v[68:69], v[66:67], 0, s[28:29]
	v_lshl_add_u64 v[78:79], v[198:199], 0, v[78:79]
	v_cndmask_b32_e32 v79, v79, v69, vcc
	v_cndmask_b32_e32 v78, v78, v68, vcc
	v_min_i32_e32 v82, 0x187, v82
	global_load_dwordx4 v[118:121], v[66:67], off offset:128
	global_load_dwordx4 v[122:125], v[66:67], off
	s_nop 0
	global_load_dwordx4 v[66:69], v[78:79], off offset:128
	s_nop 0
	global_load_dwordx4 v[78:81], v[78:79], off
	v_ashrrev_i32_e32 v83, 31, v82
	v_lshl_add_u64 v[82:83], v[82:83], 2, s[30:31]
	global_load_dword v229, v[82:83], off
	v_subrev_u32_e32 v90, 40, v222
	v_mov_b32_e32 v90, v248
	v_cmp_lt_i32_e32 vcc, s19, v90
	v_min_i32_e32 v82, 0x182, v90
	s_nop 0
	v_cndmask_b32_e64 v83, 0, 1, vcc
	v_cmp_gt_i32_e32 vcc, s23, v90
	s_nop 1
	v_cndmask_b32_e32 v83, 2, v83, vcc
	v_mul_i32_i24_e32 v84, 0xffffff7f, v83
	v_lshlrev_b32_e32 v83, 1, v83
	v_add_lshl_u32 v82, v84, v82, v83
	v_sub_u32_e32 v84, s18, v82
	v_cmp_lt_i32_e32 vcc, s26, v84
	v_cmp_gt_i32_e64 s[0:1], s17, v84
	s_and_saveexec_b64 s[14:15], s[0:1]
	s_xor_b64 s[0:1], exec, s[14:15]
	v_ashrrev_i32_e32 v85, 31, v84
	v_lshlrev_b64 v[86:87], 11, v[84:85]
	v_lshl_add_u64 v[82:83], v[194:195], 0, v[86:87]
	s_andn2_saveexec_b64 s[0:1], s[0:1]
	v_add_u32_e32 v82, 0xfffff800, v84
	v_mov_b32_e32 v85, v157
	v_mad_u64_u32 v[82:83], s[14:15], v82, s27, v[196:197]
	v_lshlrev_b64 v[86:87], 11, v[84:85]
	s_or_b64 exec, exec, s[0:1]
	v_lshl_add_u64 v[84:85], v[82:83], 0, s[28:29]
	v_lshl_add_u64 v[86:87], v[198:199], 0, v[86:87]
	v_cndmask_b32_e32 v85, v87, v85, vcc
	v_cndmask_b32_e32 v84, v86, v84, vcc
	global_load_dwordx4 v[134:137], v[82:83], off offset:128
	global_load_dwordx4 v[138:141], v[82:83], off
	global_load_dwordx4 v[86:89], v[84:85], off offset:128
	global_load_dwordx4 v[94:97], v[84:85], off
	v_min_i32_e32 v82, 0x187, v90
	v_ashrrev_i32_e32 v83, 31, v82
	v_lshl_add_u64 v[82:83], v[82:83], 2, s[30:31]
	global_load_dword v230, v[82:83], off
	v_subrev_u32_e32 v92, 32, v222
	v_mov_b32_e32 v92, v249
	v_cmp_lt_i32_e32 vcc, s19, v92
	v_min_i32_e32 v82, 0x182, v92
	s_nop 0
	v_cndmask_b32_e64 v83, 0, 1, vcc
	v_cmp_gt_i32_e32 vcc, s23, v92
	s_nop 1
	v_cndmask_b32_e32 v83, 2, v83, vcc
	v_mul_i32_i24_e32 v84, 0xffffff7f, v83
	v_lshlrev_b32_e32 v83, 1, v83
	v_add_lshl_u32 v82, v84, v82, v83
	v_sub_u32_e32 v84, s18, v82
	v_cmp_lt_i32_e32 vcc, s26, v84
	v_cmp_gt_i32_e64 s[0:1], s17, v84
; __device__ __forceinline__ void p_attn_sample(const float* P, const float* ck, const float* cv, const float* relb, bf16* heads, const float* sbt, unsigned* qctr, volatile LAS unsigned* slot, int wave, int lane_in) {
;     ...
;         SLOADB(ak0, ak1, av0, av1, ab, 0)
; #pragma unroll 1
;         for (int it0 = 0; it0 < 48; it0 += 8) {
;             SLOADB(bk0, bk1, bv0, bv1, bbv, it0 + 4)
;             SPROCB(ak0, ak1, av0, av1, ab)
	s_and_saveexec_b64 s[14:15], s[0:1]
	s_xor_b64 s[0:1], exec, s[14:15]
	v_ashrrev_i32_e32 v85, 31, v84
	v_lshlrev_b64 v[90:91], 11, v[84:85]
	v_lshl_add_u64 v[82:83], v[194:195], 0, v[90:91]
	s_andn2_saveexec_b64 s[0:1], s[0:1]
	v_add_u32_e32 v82, 0xfffff800, v84
	v_mov_b32_e32 v85, v157
	v_mad_u64_u32 v[82:83], s[14:15], v82, s27, v[196:197]
	v_lshlrev_b64 v[90:91], 11, v[84:85]
	s_or_b64 exec, exec, s[0:1]
	v_lshl_add_u64 v[84:85], v[82:83], 0, s[28:29]
	v_lshl_add_u64 v[90:91], v[198:199], 0, v[90:91]
	v_cndmask_b32_e32 v85, v91, v85, vcc
	v_cndmask_b32_e32 v84, v90, v84, vcc
	global_load_dwordx4 v[142:145], v[82:83], off offset:128
	global_load_dwordx4 v[146:149], v[82:83], off
	global_load_dwordx4 v[110:113], v[84:85], off offset:128
	global_load_dwordx4 v[126:129], v[84:85], off
	v_min_i32_e32 v82, 0x187, v92
	v_ashrrev_i32_e32 v83, 31, v82
	v_lshl_add_u64 v[82:83], v[82:83], 2, s[30:31]
	global_load_dword v231, v[82:83], off
	v_mov_b32_e32 v82, v15
	v_mov_b32_e32 v15, v17
	v_mov_b32_e32 v83, v16
	v_pk_mul_f32 v[14:15], v[210:211], v[14:15]
	v_pk_mul_f32 v[12:13], v[202:203], v[12:13]
	v_pk_mul_f32 v[10:11], v[200:201], v[10:11]
	v_pk_fma_f32 v[14:15], v[208:209], v[82:83], v[14:15]
	v_mov_b32_e32 v16, v12
	v_mov_b32_e32 v17, v10
	v_mov_b32_e32 v10, v13
	v_pk_add_f32 v[10:11], v[16:17], v[10:11]
	v_add_f32_e32 v12, v14, v15
	v_add_f32_e32 v11, v11, v12
	v_add_f32_e32 v10, v10, v11
	v_mov_b32_e32 v11, v24
	v_pk_mul_f32 v[14:15], v[200:201], v[18:19]
	v_add_f32_dpp v10, v10, v10 quad_perm:[1,0,3,2] row_mask:0xf bank_mask:0xf bound_ctrl:1
	v_mov_b32_e32 v17, v14
	v_subrev_u32_e32 v18, 24, v222
	v_mov_b32_e32 v18, v250
	v_add_f32_dpp v235, v10, v10 quad_perm:[2,3,0,1] row_mask:0xf bank_mask:0xf bound_ctrl:1
	v_mov_b32_e32 v10, v23
	v_mov_b32_e32 v23, v25
	v_pk_mul_f32 v[12:13], v[210:211], v[22:23]
	v_cmp_lt_i32_e32 vcc, s19, v18
	v_pk_fma_f32 v[10:11], v[208:209], v[10:11], v[12:13]
	v_pk_mul_f32 v[12:13], v[202:203], v[20:21]
	v_add_f32_e32 v10, v10, v11
	v_mov_b32_e32 v16, v12
	v_mov_b32_e32 v14, v13
	v_pk_add_f32 v[12:13], v[16:17], v[14:15]
	v_mov_b32_e32 v11, v32
	v_add_f32_e32 v10, v13, v10
	v_add_f32_e32 v10, v12, v10
	v_pk_mul_f32 v[14:15], v[200:201], v[26:27]
	v_mov_b32_e32 v236, 0
	v_add_f32_dpp v10, v10, v10 quad_perm:[1,0,3,2] row_mask:0xf bank_mask:0xf bound_ctrl:1
	v_mov_b32_e32 v17, v14
	v_mov_b32_e32 v238, 0
	v_add_f32_dpp v237, v10, v10 quad_perm:[2,3,0,1] row_mask:0xf bank_mask:0xf bound_ctrl:1
	v_mov_b32_e32 v10, v31
	v_mov_b32_e32 v31, v33
	v_pk_mul_f32 v[12:13], v[210:211], v[30:31]
	v_mov_b32_e32 v240, 0
	v_pk_fma_f32 v[10:11], v[208:209], v[10:11], v[12:13]
	v_pk_mul_f32 v[12:13], v[202:203], v[28:29]
	v_add_f32_e32 v10, v10, v11
	v_mov_b32_e32 v16, v12
	v_mov_b32_e32 v14, v13
	v_pk_add_f32 v[12:13], v[16:17], v[14:15]
	s_waitcnt vmcnt(23)
	v_mov_b32_e32 v11, v76
	v_add_f32_e32 v10, v13, v10
	v_add_f32_e32 v10, v12, v10
	v_pk_mul_f32 v[14:15], v[200:201], v[70:71]
	v_mov_b32_dpp v236, v235 row_half_mirror row_mask:0xf bank_mask:0xf
	v_add_f32_dpp v10, v10, v10 quad_perm:[1,0,3,2] row_mask:0xf bank_mask:0xf bound_ctrl:1
	v_mov_b32_e32 v17, v14
	v_mov_b32_dpp v238, v237 row_half_mirror row_mask:0xf bank_mask:0xf
	v_add_f32_dpp v239, v10, v10 quad_perm:[2,3,0,1] row_mask:0xf bank_mask:0xf bound_ctrl:1
	v_mov_b32_e32 v10, v75
	v_mov_b32_e32 v75, v77
	v_pk_mul_f32 v[12:13], v[210:211], v[74:75]
	v_mov_b32_e32 v77, 0
	v_pk_fma_f32 v[10:11], v[208:209], v[10:11], v[12:13]
	v_pk_mul_f32 v[12:13], v[202:203], v[72:73]
	v_add_f32_e32 v10, v10, v11
	v_mov_b32_e32 v16, v12
	v_mov_b32_e32 v14, v13
	v_pk_add_f32 v[12:13], v[16:17], v[14:15]
	v_cndmask_b32_e64 v11, 0, 1, vcc
	v_add_f32_e32 v10, v13, v10
	v_add_f32_e32 v10, v12, v10
	v_cmp_gt_i32_e32 vcc, s23, v18
	v_mov_b32_dpp v240, v239 row_half_mirror row_mask:0xf bank_mask:0xf
	v_add_f32_dpp v10, v10, v10 quad_perm:[1,0,3,2] row_mask:0xf bank_mask:0xf bound_ctrl:1
	v_cndmask_b32_e32 v11, 2, v11, vcc
	v_mul_i32_i24_e32 v12, 0xffffff7f, v11
	v_add_f32_dpp v76, v10, v10 quad_perm:[2,3,0,1] row_mask:0xf bank_mask:0xf bound_ctrl:1
	v_min_i32_e32 v10, 0x182, v18
	v_lshlrev_b32_e32 v11, 1, v11
	v_add_lshl_u32 v10, v12, v10, v11
	v_sub_u32_e32 v156, s18, v10
	v_mov_b32_dpp v77, v76 row_half_mirror row_mask:0xf bank_mask:0xf
	v_cmp_lt_i32_e32 vcc, s26, v156
	v_cmp_gt_i32_e64 s[0:1], s17, v156
	s_and_saveexec_b64 s[14:15], s[0:1]
	s_xor_b64 s[0:1], exec, s[14:15]
	v_ashrrev_i32_e32 v11, 31, v156
	v_mov_b32_e32 v10, v156
	v_lshlrev_b64 v[10:11], 11, v[10:11]
	v_lshl_add_u64 v[14:15], v[194:195], 0, v[10:11]
	s_andn2_saveexec_b64 s[0:1], s[0:1]
	v_add_u32_e32 v10, 0xfffff800, v156
	v_mad_u64_u32 v[14:15], s[14:15], v10, s27, v[196:197]
	v_lshlrev_b64 v[10:11], 11, v[156:157]
	s_or_b64 exec, exec, s[0:1]
	v_lshl_add_u64 v[12:13], v[14:15], 0, s[28:29]
	v_lshl_add_u64 v[10:11], v[198:199], 0, v[10:11]
	v_min_i32_e32 v18, 0x187, v18
	v_cndmask_b32_e32 v21, v11, v13, vcc
	v_cndmask_b32_e32 v20, v10, v12, vcc
	global_load_dwordx4 v[10:13], v[14:15], off offset:128
	s_nop 0
	global_load_dwordx4 v[14:17], v[14:15], off
	s_nop 0
	global_load_dwordx4 v[90:93], v[20:21], off offset:128
	global_load_dwordx4 v[150:153], v[20:21], off
	v_ashrrev_i32_e32 v19, 31, v18
	v_lshl_add_u64 v[18:19], v[18:19], 2, s[30:31]
	global_load_dword v232, v[18:19], off
	v_add_u32_e32 v26, -16, v222
	v_mov_b32_e32 v26, v251
	v_cmp_lt_i32_e32 vcc, s19, v26
	v_min_i32_e32 v18, 0x182, v26
	s_nop 0
	v_cndmask_b32_e64 v19, 0, 1, vcc
	v_cmp_gt_i32_e32 vcc, s23, v26
	s_nop 1
	v_cndmask_b32_e32 v19, 2, v19, vcc
	v_mul_i32_i24_e32 v20, 0xffffff7f, v19
	v_lshlrev_b32_e32 v19, 1, v19
	v_add_lshl_u32 v18, v20, v18, v19
; __device__ __forceinline__ void p_attn_sample(const float* P, const float* ck, const float* cv, const float* relb, bf16* heads, const float* sbt, unsigned* qctr, volatile LAS unsigned* slot, int wave, int lane_in) {
;     ...
;         SLOADB(ak0, ak1, av0, av1, ab, 0)
; #pragma unroll 1
;         for (int it0 = 0; it0 < 48; it0 += 8) {
;             SLOADB(bk0, bk1, bv0, bv1, bbv, it0 + 4)
;             SPROCB(ak0, ak1, av0, av1, ab)
;             SLOADB(ak0, ak1, av0, av1, ab, it0 + 8)
;             SPROCB(bk0, bk1, bv0, bv1, bbv)
	v_sub_u32_e32 v18, s18, v18
	v_cmp_lt_i32_e32 vcc, s26, v18
	v_cmp_gt_i32_e64 s[0:1], s17, v18
	s_and_saveexec_b64 s[14:15], s[0:1]
	s_xor_b64 s[0:1], exec, s[14:15]
	v_ashrrev_i32_e32 v19, 31, v18
	v_lshlrev_b64 v[20:21], 11, v[18:19]
	v_lshl_add_u64 v[22:23], v[194:195], 0, v[20:21]
	s_andn2_saveexec_b64 s[0:1], s[0:1]
	v_add_u32_e32 v19, 0xfffff800, v18
	v_mad_u64_u32 v[22:23], s[14:15], v19, s27, v[196:197]
	v_mov_b32_e32 v19, v157
	v_lshlrev_b64 v[20:21], 11, v[18:19]
	s_or_b64 exec, exec, s[0:1]
	v_lshl_add_u64 v[18:19], v[22:23], 0, s[28:29]
	v_lshl_add_u64 v[20:21], v[198:199], 0, v[20:21]
	v_min_i32_e32 v26, 0x187, v26
	v_cndmask_b32_e32 v29, v21, v19, vcc
	v_cndmask_b32_e32 v28, v20, v18, vcc
	global_load_dwordx4 v[18:21], v[22:23], off offset:128
	s_nop 0
	global_load_dwordx4 v[22:25], v[22:23], off
	s_nop 0
	global_load_dwordx4 v[82:85], v[28:29], off offset:128
	global_load_dwordx4 v[98:101], v[28:29], off
	v_ashrrev_i32_e32 v27, 31, v26
	v_lshl_add_u64 v[26:27], v[26:27], 2, s[30:31]
	global_load_dword v233, v[26:27], off
	v_add_u32_e32 v70, -8, v222
	v_mov_b32_e32 v70, v252
	v_cmp_lt_i32_e32 vcc, s19, v70
	v_min_i32_e32 v26, 0x182, v70
	s_nop 0
	v_cndmask_b32_e64 v27, 0, 1, vcc
	v_cmp_gt_i32_e32 vcc, s23, v70
	s_nop 1
	v_cndmask_b32_e32 v27, 2, v27, vcc
	v_mul_i32_i24_e32 v28, 0xffffff7f, v27
	v_lshlrev_b32_e32 v27, 1, v27
	v_add_lshl_u32 v26, v28, v26, v27
	v_sub_u32_e32 v26, s18, v26
	v_cmp_lt_i32_e32 vcc, s26, v26
	v_cmp_gt_i32_e64 s[0:1], s17, v26
	s_and_saveexec_b64 s[14:15], s[0:1]
	s_xor_b64 s[0:1], exec, s[14:15]
	v_ashrrev_i32_e32 v27, 31, v26
	v_lshlrev_b64 v[28:29], 11, v[26:27]
	v_lshl_add_u64 v[30:31], v[194:195], 0, v[28:29]
	s_andn2_saveexec_b64 s[0:1], s[0:1]
	v_add_u32_e32 v27, 0xfffff800, v26
	v_mad_u64_u32 v[30:31], s[14:15], v27, s27, v[196:197]
	v_mov_b32_e32 v27, v157
	v_lshlrev_b64 v[28:29], 11, v[26:27]
	s_or_b64 exec, exec, s[0:1]
	v_lshl_add_u64 v[26:27], v[30:31], 0, s[28:29]
	v_lshl_add_u64 v[28:29], v[198:199], 0, v[28:29]
	v_min_i32_e32 v70, 0x187, v70
	v_cndmask_b32_e32 v73, v29, v27, vcc
	v_cndmask_b32_e32 v72, v28, v26, vcc
	global_load_dwordx4 v[26:29], v[30:31], off offset:128
	s_nop 0
	global_load_dwordx4 v[30:33], v[30:31], off
	s_nop 0
	global_load_dwordx4 v[106:109], v[72:73], off offset:128
	global_load_dwordx4 v[130:133], v[72:73], off
	v_ashrrev_i32_e32 v71, 31, v70
	v_lshl_add_u64 v[70:71], v[70:71], 2, s[30:31]
	global_load_dword v234, v[70:71], off
	v_mov_b32_e32 v254, v253
	v_cmp_lt_i32_e32 vcc, s19, v254
	v_min_i32_e32 v70, 0x182, v254
	s_nop 0
	v_cndmask_b32_e64 v71, 0, 1, vcc
	v_cmp_gt_i32_e32 vcc, s23, v254
	s_nop 1
	v_cndmask_b32_e32 v71, 2, v71, vcc
	v_mul_i32_i24_e32 v72, 0xffffff7f, v71
	v_lshlrev_b32_e32 v71, 1, v71
	v_add_lshl_u32 v70, v72, v70, v71
	v_sub_u32_e32 v72, s18, v70
	v_cmp_lt_i32_e32 vcc, s26, v72
	v_cmp_gt_i32_e64 s[0:1], s17, v72
	s_and_saveexec_b64 s[14:15], s[0:1]
	s_xor_b64 s[0:1], exec, s[14:15]
	v_ashrrev_i32_e32 v73, 31, v72
	v_lshlrev_b64 v[70:71], 11, v[72:73]
	v_lshl_add_u64 v[74:75], v[194:195], 0, v[70:71]
	s_andn2_saveexec_b64 s[0:1], s[0:1]
	v_add_u32_e32 v70, 0xfffff800, v72
	v_mov_b32_e32 v73, v157
	v_mad_u64_u32 v[74:75], s[14:15], v70, s27, v[196:197]
	v_lshlrev_b64 v[70:71], 11, v[72:73]
	s_or_b64 exec, exec, s[0:1]
	v_add_f32_e32 v72, v235, v236
	v_add_f32_e32 v73, v227, v72
	v_max_f32_e32 v72, v224, v224
	v_max_f32_e32 v156, v72, v73
	v_sub_f32_e32 v73, v73, v156
	v_mul_f32_e32 v73, 0x3fb8aa3b, v73
	v_sub_f32_e32 v72, v224, v156
	v_exp_f32_e32 v224, v73
	v_add_f32_e32 v73, v237, v238
	v_add_f32_e32 v73, v226, v73
	v_max_f32_e32 v227, v156, v73
	v_sub_f32_e32 v73, v73, v227
	v_mul_f32_e32 v73, 0x3fb8aa3b, v73
	v_sub_f32_e32 v156, v156, v227
	v_exp_f32_e32 v236, v73
	v_add_f32_e32 v73, v239, v240
	v_mul_f32_e32 v156, 0x3fb8aa3b, v156
	v_add_f32_e32 v73, v225, v73
	v_mul_f32_e32 v72, 0x3fb8aa3b, v72
	v_exp_f32_e32 v226, v156
	v_max_f32_e32 v156, v227, v73
	v_exp_f32_e32 v72, v72
	v_sub_f32_e32 v225, v227, v156
	v_sub_f32_e32 v73, v73, v156
	v_mul_f32_e32 v225, 0x3fb8aa3b, v225
	v_mul_f32_e32 v73, 0x3fb8aa3b, v73
	v_exp_f32_e32 v238, v225
	v_exp_f32_e32 v240, v73
	v_fma_f32 v73, v223, v72, v224
	v_fma_f32 v73, v73, v226, v236
	v_pk_mul_f32 v[50:51], v[50:51], v[236:237] op_sel_hi:[1,0]
	v_fma_f32 v223, v73, v238, v240
	v_add_f32_e32 v73, v76, v77
	s_waitcnt vmcnt(35)
	v_add_f32_e32 v73, v221, v73
	v_max_f32_e32 v225, v156, v73
	v_sub_f32_e32 v73, v73, v225
	v_sub_f32_e32 v76, v156, v225
	v_mul_f32_e32 v73, 0x3fb8aa3b, v73
	v_mul_f32_e32 v76, 0x3fb8aa3b, v76
	v_exp_f32_e32 v156, v73
	v_exp_f32_e32 v242, v76
	v_pk_mul_f32 v[42:43], v[42:43], v[224:225] op_sel_hi:[1,0]
	s_add_i32 s3, s3, 8
	v_pk_fma_f32 v[42:43], v[218:219], v[72:73], v[42:43] op_sel_hi:[1,0,1]
	v_pk_mul_f32 v[6:7], v[6:7], v[156:157] op_sel_hi:[1,0]
	v_pk_fma_f32 v[42:43], v[42:43], v[226:227], v[50:51] op_sel_hi:[1,0,1]
	v_pk_mul_f32 v[50:51], v[58:59], v[240:241] op_sel_hi:[1,0]
	v_pk_mul_f32 v[8:9], v[8:9], v[156:157] op_sel_hi:[1,0]
	v_pk_fma_f32 v[42:43], v[42:43], v[238:239], v[50:51] op_sel_hi:[1,0,1]
	v_pk_mul_f32 v[2:3], v[2:3], v[156:157] op_sel_hi:[1,0]
	v_pk_fma_f32 v[42:43], v[42:43], v[242:243], v[6:7] op_sel_hi:[1,0,1]
	v_pk_mul_f32 v[6:7], v[44:45], v[224:225] op_sel_hi:[1,0]
	v_pk_mul_f32 v[44:45], v[52:53], v[236:237] op_sel_hi:[1,0]
	v_pk_fma_f32 v[6:7], v[216:217], v[72:73], v[6:7] op_sel_hi:[1,0,1]
	v_pk_mul_f32 v[4:5], v[4:5], v[156:157] op_sel_hi:[1,0]
	v_pk_fma_f32 v[6:7], v[6:7], v[226:227], v[44:45] op_sel_hi:[1,0,1]
	v_pk_mul_f32 v[44:45], v[60:61], v[240:241] op_sel_hi:[1,0]
	v_fmac_f32_e32 v156, v223, v242
	v_pk_fma_f32 v[6:7], v[6:7], v[238:239], v[44:45] op_sel_hi:[1,0,1]
	s_cmp_gt_u32 s3, 39
	v_pk_fma_f32 v[44:45], v[6:7], v[242:243], v[8:9] op_sel_hi:[1,0,1]
	v_pk_mul_f32 v[6:7], v[34:35], v[224:225] op_sel_hi:[1,0]
	v_pk_mul_f32 v[8:9], v[38:39], v[236:237] op_sel_hi:[1,0]
	v_pk_fma_f32 v[6:7], v[212:213], v[72:73], v[6:7] op_sel_hi:[1,0,1]
	v_min_i32_e32 v38, 0x187, v254
	v_pk_fma_f32 v[6:7], v[6:7], v[226:227], v[8:9] op_sel_hi:[1,0,1]
	v_pk_mul_f32 v[8:9], v[46:47], v[240:241] op_sel_hi:[1,0]
	v_ashrrev_i32_e32 v39, 31, v38
	v_pk_fma_f32 v[6:7], v[6:7], v[238:239], v[8:9] op_sel_hi:[1,0,1]
	v_lshl_add_u64 v[38:39], v[38:39], 2, s[30:31]
	v_pk_fma_f32 v[34:35], v[6:7], v[242:243], v[2:3] op_sel_hi:[1,0,1]
	v_pk_mul_f32 v[2:3], v[36:37], v[224:225] op_sel_hi:[1,0]
	v_pk_mul_f32 v[6:7], v[40:41], v[236:237] op_sel_hi:[1,0]
	v_pk_fma_f32 v[2:3], v[214:215], v[72:73], v[2:3] op_sel_hi:[1,0,1]
	s_waitcnt vmcnt(33)
; __device__ __forceinline__ void p_attn_sample(const float* P, const float* ck, const float* cv, const float* relb, bf16* heads, const float* sbt, unsigned* qctr, volatile LAS unsigned* slot, int wave, int lane_in) {
;     ...
;         SLOADB(ak0, ak1, av0, av1, ab, 0)
; #pragma unroll 1
;         for (int it0 = 0; it0 < 48; it0 += 8) {
;             SLOADB(bk0, bk1, bv0, bv1, bbv, it0 + 4)
;             SPROCB(ak0, ak1, av0, av1, ab)
;             SLOADB(ak0, ak1, av0, av1, ab, it0 + 8)
;             SPROCB(bk0, bk1, bv0, bv1, bbv)
	v_pk_mul_f32 v[40:41], v[204:205], v[114:115]
	v_pk_fma_f32 v[2:3], v[2:3], v[226:227], v[6:7] op_sel_hi:[1,0,1]
	v_pk_mul_f32 v[6:7], v[48:49], v[240:241] op_sel_hi:[1,0]
	v_add_u32_e32 v222, 64, v222
	v_pk_fma_f32 v[2:3], v[2:3], v[238:239], v[6:7] op_sel_hi:[1,0,1]
	s_nop 0
	v_pk_fma_f32 v[36:37], v[2:3], v[242:243], v[4:5] op_sel_hi:[1,0,1]
	v_lshl_add_u64 v[2:3], v[74:75], 0, s[28:29]
	v_lshl_add_u64 v[4:5], v[198:199], 0, v[70:71]
	v_cndmask_b32_e32 v7, v5, v3, vcc
	v_cndmask_b32_e32 v6, v4, v2, vcc
	global_load_dwordx4 v[70:73], v[74:75], off offset:128
	s_nop 0
	global_load_dwordx4 v[74:77], v[74:75], off
	s_nop 0
	global_load_dwordx4 v[2:5], v[6:7], off offset:128
	s_nop 0
	global_load_dwordx4 v[6:9], v[6:7], off
	s_nop 0
	global_load_dword v221, v[38:39], off
	v_pk_mul_f32 v[38:39], v[206:207], v[116:117]
	s_nop 0
	v_pk_mov_b32 v[46:47], v[40:41], v[38:39] op_sel:[1,0]
	v_mov_b32_e32 v41, v39
	v_pk_add_f32 v[38:39], v[46:47], v[40:41]
	v_pk_mul_f32 v[40:41], v[202:203], v[104:105]
	v_pk_mul_f32 v[46:47], v[200:201], v[102:103]
	v_mov_b32_e32 v48, v40
	v_mov_b32_e32 v49, v46
	v_mov_b32_e32 v46, v41
	v_pk_add_f32 v[40:41], v[48:49], v[46:47]
	v_add_f32_e32 v38, v38, v39
	v_add_f32_e32 v38, v38, v41
	v_add_f32_e32 v38, v40, v38
	s_waitcnt vmcnt(33)
	v_pk_mul_f32 v[46:47], v[206:207], v[124:125]
	v_pk_mul_f32 v[48:49], v[204:205], v[122:123]
	v_add_f32_dpp v38, v38, v38 quad_perm:[1,0,3,2] row_mask:0xf bank_mask:0xf bound_ctrl:1
	v_pk_mov_b32 v[50:51], v[48:49], v[46:47] op_sel:[1,0]
	v_mov_b32_e32 v49, v47
	v_add_f32_dpp v38, v38, v38 quad_perm:[2,3,0,1] row_mask:0xf bank_mask:0xf bound_ctrl:1
	v_pk_add_f32 v[46:47], v[50:51], v[48:49]
	v_pk_mul_f32 v[48:49], v[202:203], v[120:121]
	v_add_f32_dpp v38, v38, v38 row_half_mirror row_mask:0xf bank_mask:0xf bound_ctrl:1
	v_add_f32_e32 v39, v228, v38
	v_max_f32_e32 v41, v225, v39
	v_sub_f32_e32 v39, v39, v41
	v_pk_mul_f32 v[50:51], v[200:201], v[118:119]
	v_mul_f32_e32 v39, 0x3fb8aa3b, v39
	v_mov_b32_e32 v52, v48
	v_mov_b32_e32 v53, v50
	v_mov_b32_e32 v50, v49
	v_exp_f32_e32 v40, v39
	v_pk_add_f32 v[48:49], v[52:53], v[50:51]
	v_add_f32_e32 v39, v46, v47
	v_add_f32_e32 v39, v39, v49
	v_add_f32_e32 v39, v48, v39
	s_waitcnt vmcnt(28)
	v_pk_mul_f32 v[50:51], v[206:207], v[140:141]
	v_pk_mul_f32 v[52:53], v[204:205], v[138:139]
	v_add_f32_dpp v39, v39, v39 quad_perm:[1,0,3,2] row_mask:0xf bank_mask:0xf bound_ctrl:1
	v_pk_mov_b32 v[58:59], v[52:53], v[50:51] op_sel:[1,0]
	v_mov_b32_e32 v53, v51
	v_add_f32_dpp v39, v39, v39 quad_perm:[2,3,0,1] row_mask:0xf bank_mask:0xf bound_ctrl:1
	v_pk_add_f32 v[50:51], v[58:59], v[52:53]
	v_pk_mul_f32 v[52:53], v[202:203], v[136:137]
	v_add_f32_dpp v39, v39, v39 row_half_mirror row_mask:0xf bank_mask:0xf bound_ctrl:1
	v_add_f32_e32 v39, v229, v39
	v_max_f32_e32 v47, v41, v39
	v_sub_f32_e32 v39, v39, v47
	v_pk_mul_f32 v[58:59], v[200:201], v[134:135]
	v_mul_f32_e32 v39, 0x3fb8aa3b, v39
	v_mov_b32_e32 v60, v52
	v_mov_b32_e32 v61, v58
	v_mov_b32_e32 v58, v53
	v_exp_f32_e32 v48, v39
	v_pk_add_f32 v[52:53], v[60:61], v[58:59]
	v_add_f32_e32 v39, v50, v51
	v_add_f32_e32 v39, v39, v53
	v_add_f32_e32 v39, v52, v39
	v_sub_f32_e32 v38, v225, v41
	v_sub_f32_e32 v41, v41, v47
	v_add_f32_dpp v39, v39, v39 quad_perm:[1,0,3,2] row_mask:0xf bank_mask:0xf bound_ctrl:1
	v_mul_f32_e32 v41, 0x3fb8aa3b, v41
	s_waitcnt vmcnt(23)
	v_pk_mul_f32 v[58:59], v[206:207], v[148:149]
	v_add_f32_dpp v39, v39, v39 quad_perm:[2,3,0,1] row_mask:0xf bank_mask:0xf bound_ctrl:1
	v_pk_mul_f32 v[60:61], v[204:205], v[146:147]
	v_exp_f32_e32 v46, v41
	v_add_f32_dpp v39, v39, v39 row_half_mirror row_mask:0xf bank_mask:0xf bound_ctrl:1
	v_add_f32_e32 v39, v230, v39
	v_max_f32_e32 v41, v47, v39
	v_pk_mov_b32 v[102:103], v[60:61], v[58:59] op_sel:[1,0]
	v_mov_b32_e32 v61, v59
	v_sub_f32_e32 v39, v39, v41
	v_pk_add_f32 v[58:59], v[102:103], v[60:61]
	v_pk_mul_f32 v[60:61], v[202:203], v[144:145]
	v_pk_mul_f32 v[102:103], v[200:201], v[142:143]
	v_mul_f32_e32 v39, 0x3fb8aa3b, v39
	v_mov_b32_e32 v104, v60
	v_mov_b32_e32 v105, v102
	v_mov_b32_e32 v102, v61
	v_exp_f32_e32 v52, v39
	v_pk_add_f32 v[60:61], v[104:105], v[102:103]
	v_add_f32_e32 v39, v58, v59
	v_add_f32_e32 v39, v39, v61
	v_add_f32_e32 v39, v60, v39
	v_mul_f32_e32 v38, 0x3fb8aa3b, v38
	v_exp_f32_e32 v38, v38
	v_add_f32_dpp v39, v39, v39 quad_perm:[1,0,3,2] row_mask:0xf bank_mask:0xf bound_ctrl:1
	v_sub_f32_e32 v47, v47, v41
	v_mul_f32_e32 v47, 0x3fb8aa3b, v47
	v_add_f32_dpp v39, v39, v39 quad_perm:[2,3,0,1] row_mask:0xf bank_mask:0xf bound_ctrl:1
	v_exp_f32_e32 v50, v47
	s_nop 0
	v_add_f32_dpp v39, v39, v39 row_half_mirror row_mask:0xf bank_mask:0xf bound_ctrl:1
	s_waitcnt vmcnt(20)
; __device__ __forceinline__ void p_attn_sample(const float* P, const float* ck, const float* cv, const float* relb, bf16* heads, const float* sbt, unsigned* qctr, volatile LAS unsigned* slot, int wave, int lane_in) {
;     ...
;         SLOADB(ak0, ak1, av0, av1, ab, 0)
; #pragma unroll 1
;         for (int it0 = 0; it0 < 48; it0 += 8) {
;             SLOADB(bk0, bk1, bv0, bv1, bbv, it0 + 4)
;             SPROCB(ak0, ak1, av0, av1, ab)
;             SLOADB(ak0, ak1, av0, av1, ab, it0 + 8)
;             SPROCB(bk0, bk1, bv0, bv1, bbv)
;         }
;         SPROCB(ak0, ak1, av0, av1, ab)
	v_add_f32_e32 v39, v231, v39
	v_max_f32_e32 v224, v41, v39
	v_sub_f32_e32 v39, v39, v224
	v_mul_f32_e32 v39, 0x3fb8aa3b, v39
	v_sub_f32_e32 v41, v41, v224
	v_exp_f32_e32 v60, v39
	v_fma_f32 v39, v156, v38, v40
	v_mul_f32_e32 v41, 0x3fb8aa3b, v41
	v_fma_f32 v39, v39, v46, v48
	v_exp_f32_e32 v58, v41
	v_fma_f32 v39, v39, v50, v52
	v_pk_mul_f32 v[62:63], v[62:63], v[40:41] op_sel_hi:[1,0]
	v_fma_f32 v223, v39, v58, v60
	v_pk_fma_f32 v[42:43], v[42:43], v[38:39], v[62:63] op_sel_hi:[1,0,1]
	v_pk_mul_f32 v[62:63], v[78:79], v[48:49] op_sel_hi:[1,0]
	s_nop 0
	v_pk_fma_f32 v[42:43], v[42:43], v[46:47], v[62:63] op_sel_hi:[1,0,1]
	v_pk_mul_f32 v[62:63], v[94:95], v[52:53] op_sel_hi:[1,0]
	s_nop 0
	v_pk_fma_f32 v[42:43], v[42:43], v[50:51], v[62:63] op_sel_hi:[1,0,1]
	v_pk_mul_f32 v[62:63], v[126:127], v[60:61] op_sel_hi:[1,0]
	s_nop 0
	v_pk_fma_f32 v[218:219], v[42:43], v[58:59], v[62:63] op_sel_hi:[1,0,1]
	v_pk_mul_f32 v[42:43], v[64:65], v[40:41] op_sel_hi:[1,0]
	s_nop 0
	v_pk_fma_f32 v[42:43], v[44:45], v[38:39], v[42:43] op_sel_hi:[1,0,1]
	v_pk_mul_f32 v[44:45], v[80:81], v[48:49] op_sel_hi:[1,0]
	s_nop 0
	v_pk_fma_f32 v[42:43], v[42:43], v[46:47], v[44:45] op_sel_hi:[1,0,1]
	v_pk_mul_f32 v[44:45], v[96:97], v[52:53] op_sel_hi:[1,0]
	s_nop 0
	v_pk_fma_f32 v[42:43], v[42:43], v[50:51], v[44:45] op_sel_hi:[1,0,1]
	v_pk_mul_f32 v[44:45], v[128:129], v[60:61] op_sel_hi:[1,0]
	s_nop 0
	v_pk_fma_f32 v[216:217], v[42:43], v[58:59], v[44:45] op_sel_hi:[1,0,1]
	v_pk_mul_f32 v[42:43], v[54:55], v[40:41] op_sel_hi:[1,0]
	s_nop 0
	v_pk_fma_f32 v[34:35], v[34:35], v[38:39], v[42:43] op_sel_hi:[1,0,1]
	v_pk_mul_f32 v[42:43], v[66:67], v[48:49] op_sel_hi:[1,0]
	s_nop 0
	v_pk_fma_f32 v[34:35], v[34:35], v[46:47], v[42:43] op_sel_hi:[1,0,1]
	v_pk_mul_f32 v[42:43], v[86:87], v[52:53] op_sel_hi:[1,0]
	s_nop 0
	v_pk_fma_f32 v[34:35], v[34:35], v[50:51], v[42:43] op_sel_hi:[1,0,1]
	v_pk_mul_f32 v[42:43], v[110:111], v[60:61] op_sel_hi:[1,0]
	s_nop 0
	v_pk_fma_f32 v[212:213], v[34:35], v[58:59], v[42:43] op_sel_hi:[1,0,1]
	v_pk_mul_f32 v[34:35], v[56:57], v[40:41] op_sel_hi:[1,0]
	s_nop 0
	v_pk_fma_f32 v[34:35], v[36:37], v[38:39], v[34:35] op_sel_hi:[1,0,1]
	v_pk_mul_f32 v[36:37], v[68:69], v[48:49] op_sel_hi:[1,0]
	s_nop 0
	v_pk_fma_f32 v[34:35], v[34:35], v[46:47], v[36:37] op_sel_hi:[1,0,1]
	v_pk_mul_f32 v[36:37], v[88:89], v[52:53] op_sel_hi:[1,0]
	s_nop 0
	v_pk_fma_f32 v[34:35], v[34:35], v[50:51], v[36:37] op_sel_hi:[1,0,1]
	v_pk_mul_f32 v[36:37], v[112:113], v[60:61] op_sel_hi:[1,0]
	s_nop 0
	v_pk_fma_f32 v[214:215], v[34:35], v[58:59], v[36:37] op_sel_hi:[1,0,1]
	s_cbranch_scc1 .LBB0_1417
	s_waitcnt vmcnt(17)
	v_mov_b64_e32 v[34:35], v[90:91]
	s_waitcnt vmcnt(12)
	v_mov_b64_e32 v[38:39], v[82:83]
	s_waitcnt vmcnt(7)
	v_mov_b64_e32 v[46:47], v[106:107]
	v_mov_b64_e32 v[42:43], v[150:151]
	v_mov_b64_e32 v[50:51], v[98:99]
	s_waitcnt vmcnt(6)
	v_mov_b64_e32 v[58:59], v[130:131]
	v_mov_b64_e32 v[36:37], v[92:93]
	v_mov_b64_e32 v[40:41], v[84:85]
	v_mov_b64_e32 v[48:49], v[108:109]
	v_mov_b64_e32 v[44:45], v[152:153]
	v_mov_b64_e32 v[52:53], v[100:101]
	v_mov_b64_e32 v[60:61], v[132:133]
	s_waitcnt vmcnt(5)
	v_mov_b32_e32 v225, v234
	v_mov_b32_e32 v226, v233
	v_mov_b32_e32 v227, v232
	s_branch .LBB0_1383
.LBB0_1417:
	s_waitcnt vmcnt(18)
	v_pk_mul_f32 v[16:17], v[206:207], v[16:17]
	v_pk_mul_f32 v[14:15], v[204:205], v[14:15]
	v_pk_mul_f32 v[12:13], v[202:203], v[12:13]
	v_pk_mov_b32 v[34:35], v[14:15], v[16:17] op_sel:[1,0]
	v_mov_b32_e32 v15, v17
	v_pk_mul_f32 v[10:11], v[200:201], v[10:11]
	v_pk_add_f32 v[14:15], v[34:35], v[14:15]
	v_mov_b32_e32 v16, v12
	v_mov_b32_e32 v17, v10
	v_mov_b32_e32 v10, v13
	v_pk_add_f32 v[10:11], v[16:17], v[10:11]
	v_add_f32_e32 v12, v14, v15
	v_add_f32_e32 v11, v12, v11
	v_add_f32_e32 v10, v10, v11
	s_waitcnt vmcnt(13)
	v_pk_mul_f32 v[24:25], v[206:207], v[24:25]
	v_pk_mul_f32 v[22:23], v[204:205], v[22:23]
	v_add_f32_dpp v10, v10, v10 quad_perm:[1,0,3,2] row_mask:0xf bank_mask:0xf bound_ctrl:1
	v_pk_mov_b32 v[34:35], v[22:23], v[24:25] op_sel:[1,0]
	v_mov_b32_e32 v23, v25
	v_add_f32_dpp v10, v10, v10 quad_perm:[2,3,0,1] row_mask:0xf bank_mask:0xf bound_ctrl:1
	v_pk_mul_f32 v[20:21], v[202:203], v[20:21]
	v_pk_mul_f32 v[18:19], v[200:201], v[18:19]
	v_add_f32_dpp v10, v10, v10 row_half_mirror row_mask:0xf bank_mask:0xf bound_ctrl:1
	v_pk_add_f32 v[22:23], v[34:35], v[22:23]
	v_mov_b32_e32 v24, v20
	v_mov_b32_e32 v25, v18
	v_mov_b32_e32 v18, v21
	v_add_f32_e32 v11, v232, v10
	v_max_f32_e32 v10, v224, v224
	v_pk_add_f32 v[18:19], v[24:25], v[18:19]
	v_add_f32_e32 v20, v22, v23
	v_max_f32_e32 v13, v10, v11
	v_add_f32_e32 v19, v20, v19
	v_sub_f32_e32 v11, v11, v13
	v_add_f32_e32 v18, v18, v19
	v_mul_f32_e32 v11, 0x3fb8aa3b, v11
	v_exp_f32_e32 v12, v11
	v_add_f32_dpp v18, v18, v18 quad_perm:[1,0,3,2] row_mask:0xf bank_mask:0xf bound_ctrl:1
	v_sub_f32_e32 v10, v224, v13
	s_waitcnt vmcnt(8)
	v_pk_mul_f32 v[24:25], v[204:205], v[30:31]
	v_add_f32_dpp v18, v18, v18 quad_perm:[2,3,0,1] row_mask:0xf bank_mask:0xf bound_ctrl:1
	v_pk_mul_f32 v[14:15], v[150:151], v[12:13] op_sel_hi:[1,0]
	v_pk_mul_f32 v[16:17], v[152:153], v[12:13] op_sel_hi:[1,0]
	v_add_f32_dpp v18, v18, v18 row_half_mirror row_mask:0xf bank_mask:0xf bound_ctrl:1
	v_add_f32_e32 v18, v233, v18
	v_max_f32_e32 v21, v13, v18
	v_sub_f32_e32 v13, v13, v21
	v_mul_f32_e32 v13, 0x3fb8aa3b, v13
	v_exp_f32_e32 v20, v13
	v_sub_f32_e32 v13, v18, v21
	v_pk_mul_f32 v[18:19], v[206:207], v[32:33]
	v_pk_mul_f32 v[26:27], v[200:201], v[26:27]
	v_pk_mov_b32 v[30:31], v[24:25], v[18:19] op_sel:[1,0]
	v_mov_b32_e32 v25, v19
	v_pk_add_f32 v[18:19], v[30:31], v[24:25]
	v_pk_mul_f32 v[24:25], v[202:203], v[28:29]
	v_mul_f32_e32 v13, 0x3fb8aa3b, v13
	v_mov_b32_e32 v28, v24
	v_mov_b32_e32 v29, v26
	v_mov_b32_e32 v26, v25
	v_exp_f32_e32 v22, v13
	v_pk_add_f32 v[24:25], v[28:29], v[26:27]
	v_add_f32_e32 v13, v18, v19
	v_add_f32_e32 v13, v13, v25
	v_add_f32_e32 v13, v24, v13
	s_waitcnt vmcnt(3)
; __device__ __forceinline__ unsigned pk2(float lo, float hi) { f32x2_p v = {lo, hi}; bf16x2_p b = __builtin_convertvector(v, bf16x2_p); return __builtin_bit_cast(unsigned, b); }
; __device__ __forceinline__ void p_attn_sample(const float* P, const float* ck, const float* cv, const float* relb, bf16* heads, const float* sbt, unsigned* qctr, volatile LAS unsigned* slot, int wave, int lane_in) {
;     ...
;         SPROCB(ak0, ak1, av0, av1, ab)
;     ...
;         float mt = fmaxf(mx, __shfl_xor(mx, 8)); mt = fmaxf(mt, __shfl_xor(mt, 16)); mt = fmaxf(mt, __shfl_xor(mt, 32));
;         const float fs = __expf(mx - mt); sum *= fs;
;         sum += __shfl_xor(sum, 8); sum += __shfl_xor(sum, 16); sum += __shfl_xor(sum, 32);
; #pragma unroll
;         for (int j = 0; j < 8; ++j) { acc[j] *= fs; acc[j] += __shfl_xor(acc[j], 8); acc[j] += __shfl_xor(acc[j], 16); acc[j] += __shfl_xor(acc[j], 32); }
;         if (g == 0) { const float inv = 1.0f / sum; v4u o; o.x = pk2(acc[0] * inv, acc[1] * inv); o.y = pk2(acc[2] * inv, acc[3] * inv); o.z = pk2(acc[4] * inv, acc[5] * inv); o.w = pk2(acc[6] * inv, acc[7] * inv);
	v_pk_mul_f32 v[18:19], v[206:207], v[76:77]
	v_pk_mul_f32 v[24:25], v[204:205], v[74:75]
	v_add_f32_dpp v13, v13, v13 quad_perm:[1,0,3,2] row_mask:0xf bank_mask:0xf bound_ctrl:1
	v_pk_mov_b32 v[26:27], v[24:25], v[18:19] op_sel:[1,0]
	v_mov_b32_e32 v25, v19
	v_pk_add_f32 v[18:19], v[26:27], v[24:25]
	v_pk_mul_f32 v[24:25], v[202:203], v[72:73]
	v_pk_mul_f32 v[26:27], v[200:201], v[70:71]
	v_mov_b32_e32 v28, v24
	v_mov_b32_e32 v29, v26
	v_mov_b32_e32 v26, v25
	v_pk_add_f32 v[24:25], v[28:29], v[26:27]
	v_add_f32_e32 v18, v18, v19
	v_add_f32_e32 v18, v18, v25
	v_add_f32_e32 v18, v24, v18
	v_add_f32_dpp v13, v13, v13 quad_perm:[2,3,0,1] row_mask:0xf bank_mask:0xf bound_ctrl:1
	v_and_b32_e32 v25, 64, v220
	v_add_f32_dpp v18, v18, v18 quad_perm:[1,0,3,2] row_mask:0xf bank_mask:0xf bound_ctrl:1
	v_add_f32_dpp v13, v13, v13 row_half_mirror row_mask:0xf bank_mask:0xf bound_ctrl:1
	v_xor_b32_e32 v24, 8, v220
	v_add_f32_dpp v18, v18, v18 quad_perm:[2,3,0,1] row_mask:0xf bank_mask:0xf bound_ctrl:1
	v_add_u32_e32 v25, 64, v25
	v_add_f32_e32 v13, v234, v13
	v_add_f32_dpp v18, v18, v18 row_half_mirror row_mask:0xf bank_mask:0xf bound_ctrl:1
	v_cmp_lt_i32_e32 vcc, v24, v25
	v_max_f32_e32 v23, v21, v13
	s_waitcnt vmcnt(0)
	v_add_f32_e32 v18, v221, v18
	v_cndmask_b32_e32 v24, v220, v24, vcc
	v_max_f32_e32 v19, v23, v18
	v_lshlrev_b32_e32 v27, 2, v24
	ds_bpermute_b32 v26, v27, v19
	v_sub_f32_e32 v21, v21, v23
	v_mul_f32_e32 v21, 0x3fb8aa3b, v21
	v_exp_f32_e32 v24, v21
	v_sub_f32_e32 v13, v13, v23
	s_waitcnt lgkmcnt(0)
	v_max_f32_e32 v21, v26, v26
	v_xor_b32_e32 v26, 16, v220
	v_cmp_lt_i32_e32 vcc, v26, v25
	v_max_f32_e32 v21, v19, v21
	v_mul_f32_e32 v13, 0x3fb8aa3b, v13
	v_cndmask_b32_e32 v26, v220, v26, vcc
	v_lshlrev_b32_e32 v29, 2, v26
	ds_bpermute_b32 v28, v29, v21
	v_exp_f32_e32 v26, v13
	v_sub_f32_e32 v13, v23, v19
	v_mul_f32_e32 v13, 0x3fb8aa3b, v13
	v_mul_f32_e32 v10, 0x3fb8aa3b, v10
	s_waitcnt lgkmcnt(0)
	v_max_f32_e32 v23, v28, v28
	v_max_f32_e32 v21, v21, v23
	v_xor_b32_e32 v23, 32, v220
	v_cmp_lt_i32_e32 vcc, v23, v25
	v_exp_f32_e32 v28, v13
	v_sub_f32_e32 v13, v18, v19
	v_cndmask_b32_e32 v23, v220, v23, vcc
	v_lshlrev_b32_e32 v25, 2, v23
	ds_bpermute_b32 v23, v25, v21
	v_mul_f32_e32 v13, 0x3fb8aa3b, v13
	v_exp_f32_e32 v10, v10
	v_exp_f32_e32 v30, v13
	s_waitcnt lgkmcnt(0)
	v_max_f32_e32 v13, v23, v23
	v_max_f32_e32 v13, v21, v13
	v_sub_f32_e32 v13, v19, v13
	v_mul_f32_e32 v13, 0x3fb8aa3b, v13
	v_fma_f32 v11, v223, v10, v12
	v_exp_f32_e32 v32, v13
	v_pk_fma_f32 v[14:15], v[218:219], v[10:11], v[14:15] op_sel_hi:[1,0,1]
	v_pk_fma_f32 v[16:17], v[216:217], v[10:11], v[16:17] op_sel_hi:[1,0,1]
	v_fma_f32 v11, v11, v20, v22
	v_fma_f32 v11, v11, v24, v26
	v_fma_f32 v11, v11, v28, v30
	v_mul_f32_e32 v13, v11, v32
	ds_bpermute_b32 v21, v27, v13
	v_pk_mul_f32 v[18:19], v[90:91], v[12:13] op_sel_hi:[1,0]
	v_pk_mul_f32 v[12:13], v[92:93], v[12:13] op_sel_hi:[1,0]
	v_pk_fma_f32 v[34:35], v[212:213], v[10:11], v[18:19] op_sel_hi:[1,0,1]
	v_pk_fma_f32 v[12:13], v[214:215], v[10:11], v[12:13] op_sel_hi:[1,0,1]
	s_waitcnt lgkmcnt(0)
	v_fmac_f32_e32 v21, v11, v32
	v_pk_mul_f32 v[10:11], v[98:99], v[22:23] op_sel_hi:[1,0]
	v_pk_mul_f32 v[8:9], v[8:9], v[30:31] op_sel_hi:[1,0]
	v_pk_fma_f32 v[10:11], v[14:15], v[20:21], v[10:11] op_sel_hi:[1,0,1]
	v_pk_mul_f32 v[14:15], v[130:131], v[26:27] op_sel_hi:[1,0]
	v_pk_mul_f32 v[2:3], v[2:3], v[30:31] op_sel_hi:[1,0]
	v_pk_fma_f32 v[10:11], v[10:11], v[24:25], v[14:15] op_sel_hi:[1,0,1]
	v_pk_mul_f32 v[14:15], v[100:101], v[22:23] op_sel_hi:[1,0]
	v_pk_mul_f32 v[6:7], v[6:7], v[30:31] op_sel_hi:[1,0]
	v_pk_fma_f32 v[14:15], v[16:17], v[20:21], v[14:15] op_sel_hi:[1,0,1]
	v_pk_mul_f32 v[16:17], v[132:133], v[26:27] op_sel_hi:[1,0]
	v_pk_mul_f32 v[4:5], v[4:5], v[30:31] op_sel_hi:[1,0]
	v_pk_fma_f32 v[14:15], v[14:15], v[24:25], v[16:17] op_sel_hi:[1,0,1]
	v_pk_mul_f32 v[16:17], v[106:107], v[26:27] op_sel_hi:[1,0]
	v_pk_fma_f32 v[8:9], v[14:15], v[28:29], v[8:9] op_sel_hi:[1,0,1]
	v_pk_fma_f32 v[6:7], v[10:11], v[28:29], v[6:7] op_sel_hi:[1,0,1]
	v_pk_mul_f32 v[14:15], v[8:9], v[32:33] op_sel_hi:[1,0]
	ds_bpermute_b32 v14, v27, v14
	ds_bpermute_b32 v15, v27, v15
	v_pk_mul_f32 v[10:11], v[6:7], v[32:33] op_sel_hi:[1,0]
	ds_bpermute_b32 v18, v29, v21
	ds_bpermute_b32 v10, v27, v10
	ds_bpermute_b32 v11, v27, v11
	s_waitcnt lgkmcnt(3)
	v_pk_fma_f32 v[8:9], v[8:9], v[32:33], v[14:15] op_sel_hi:[1,0,1]
	ds_bpermute_b32 v14, v29, v8
	ds_bpermute_b32 v15, v29, v9
	s_waitcnt lgkmcnt(4)
	v_add_f32_e32 v18, v21, v18
	s_waitcnt lgkmcnt(2)
	v_pk_fma_f32 v[6:7], v[6:7], v[32:33], v[10:11] op_sel_hi:[1,0,1]
	ds_bpermute_b32 v10, v29, v6
	ds_bpermute_b32 v11, v29, v7
	s_waitcnt lgkmcnt(2)
	v_pk_add_f32 v[8:9], v[8:9], v[14:15]
	v_pk_mul_f32 v[14:15], v[82:83], v[22:23] op_sel_hi:[1,0]
	ds_bpermute_b32 v19, v25, v18
	v_pk_fma_f32 v[14:15], v[34:35], v[20:21], v[14:15] op_sel_hi:[1,0,1]
	s_waitcnt lgkmcnt(1)
	v_pk_add_f32 v[6:7], v[6:7], v[10:11]
	v_pk_fma_f32 v[14:15], v[14:15], v[24:25], v[16:17] op_sel_hi:[1,0,1]
	ds_bpermute_b32 v10, v25, v6
	v_pk_fma_f32 v[14:15], v[14:15], v[28:29], v[2:3] op_sel_hi:[1,0,1]
	ds_bpermute_b32 v11, v25, v7
	v_pk_mul_f32 v[2:3], v[14:15], v[32:33] op_sel_hi:[1,0]
	ds_bpermute_b32 v16, v27, v2
	ds_bpermute_b32 v17, v27, v3
	v_pk_mul_f32 v[2:3], v[84:85], v[22:23] op_sel_hi:[1,0]
	s_waitcnt lgkmcnt(0)
	v_pk_fma_f32 v[14:15], v[14:15], v[32:33], v[16:17] op_sel_hi:[1,0,1]
	v_pk_fma_f32 v[2:3], v[12:13], v[20:21], v[2:3] op_sel_hi:[1,0,1]
	v_pk_mul_f32 v[12:13], v[108:109], v[26:27] op_sel_hi:[1,0]
	ds_bpermute_b32 v16, v29, v14
	v_pk_fma_f32 v[2:3], v[2:3], v[24:25], v[12:13] op_sel_hi:[1,0,1]
	ds_bpermute_b32 v17, v29, v15
	v_pk_fma_f32 v[4:5], v[2:3], v[28:29], v[4:5] op_sel_hi:[1,0,1]
	s_nop 0
	v_pk_mul_f32 v[2:3], v[4:5], v[32:33] op_sel_hi:[1,0]
	ds_bpermute_b32 v12, v27, v2
	ds_bpermute_b32 v13, v27, v3
	ds_bpermute_b32 v2, v25, v8
	ds_bpermute_b32 v3, v25, v9
	s_waitcnt lgkmcnt(2)
	v_pk_fma_f32 v[20:21], v[4:5], v[32:33], v[12:13] op_sel_hi:[1,0,1]
	ds_bpermute_b32 v22, v29, v20
	ds_bpermute_b32 v23, v29, v21
	v_pk_add_f32 v[4:5], v[14:15], v[16:17]
	ds_bpermute_b32 v12, v25, v4
	ds_bpermute_b32 v13, v25, v5
	s_waitcnt lgkmcnt(2)
	v_pk_add_f32 v[14:15], v[20:21], v[22:23]
	ds_bpermute_b32 v16, v25, v14
	ds_bpermute_b32 v17, v25, v15
	s_and_saveexec_b64 s[0:1], s[4:5]
	s_xor_b64 s[0:1], exec, s[0:1]
	s_cbranch_execz .LBB0_1375
; __device__ __forceinline__ unsigned pk2(float lo, float hi) { f32x2_p v = {lo, hi}; bf16x2_p b = __builtin_convertvector(v, bf16x2_p); return __builtin_bit_cast(unsigned, b); }
; __device__ __forceinline__ void p_attn_sample(const float* P, const float* ck, const float* cv, const float* relb, bf16* heads, const float* sbt, unsigned* qctr, volatile LAS unsigned* slot, int wave, int lane_in) {
;     ...
;         if (g == 0) { const float inv = 1.0f / sum; v4u o; o.x = pk2(acc[0] * inv, acc[1] * inv); o.y = pk2(acc[2] * inv, acc[3] * inv); o.z = pk2(acc[4] * inv, acc[5] * inv); o.w = pk2(acc[6] * inv, acc[7] * inv);
;             *(v4u*)(heads + (size_t)m * DM + h * 64 + 8 * c) = o; }
	v_add_f32_e32 v18, v18, v19
	v_div_scale_f32 v19, s[14:15], v18, v18, 1.0
	v_rcp_f32_e32 v20, v19
	v_div_scale_f32 v21, vcc, 1.0, v18, 1.0
	v_pk_add_f32 v[6:7], v[6:7], v[10:11]
	v_fma_f32 v22, -v19, v20, 1.0
	v_fmac_f32_e32 v20, v22, v20
	v_mul_f32_e32 v22, v21, v20
	v_fma_f32 v23, -v19, v22, v21
	v_fmac_f32_e32 v22, v23, v20
	v_fma_f32 v19, -v19, v22, v21
	v_div_fmas_f32 v19, v19, v20, v22
	v_div_fixup_f32 v18, v19, v18, 1.0
	v_pk_add_f32 v[2:3], v[8:9], v[2:3]
	v_pk_mul_f32 v[6:7], v[6:7], v[18:19] op_sel_hi:[1,0]
	v_pk_mul_f32 v[2:3], v[18:19], v[2:3] op_sel_hi:[0,1]
	v_cvt_pk_bf16_f32 v6, v6, v7
	v_cvt_pk_bf16_f32 v7, v2, v3
	s_waitcnt lgkmcnt(2)
	v_pk_add_f32 v[2:3], v[4:5], v[12:13]
	s_lshl_b32 s2, s2, 11
	v_pk_mul_f32 v[2:3], v[18:19], v[2:3] op_sel_hi:[0,1]
	s_add_u32 s2, s48, s2
	v_cvt_pk_bf16_f32 v8, v2, v3
	s_waitcnt lgkmcnt(0)
	v_pk_add_f32 v[2:3], v[14:15], v[16:17]
	s_addc_u32 s3, s49, 0
	s_lshl_b32 s14, s20, 1
	v_pk_mul_f32 v[2:3], v[18:19], v[2:3] op_sel_hi:[0,1]
	s_add_u32 s2, s2, s14
	v_cvt_pk_bf16_f32 v9, v2, v3
	s_addc_u32 s3, s3, 0
	global_store_dwordx2 v154, v[6:7], s[2:3]
	global_store_dwordx2 v154, v[8:9], s[2:3] offset:64
	s_branch .LBB0_1375
